# SiLU and GLU sigmoid epilogues use a*rcp(b); S5 final step: 4-FMA recurrence, gelu as x*sigmoid(2u)
# speedup vs baseline: 1.0287x; 1.0148x over previous
; DI float siluf_(float x) { return x / (1.f + __expf(-x)); }
; template <int EPI>
; DI void gemm_tile(const GemmArgs& ga, const EpiArgs& ea, int m0, int n0, char* lds) {
;     ...
;           } else if (slot == 1 || slot == 5 || slot == 7 || slot == 9) {
; #pragma unroll
;             for (int r = 0; r < 4; ++r) v[r] = siluf_(v[r]);
.LBB0_193:
	s_and_b64 vcc, exec, s[38:39]
	s_cbranch_vccz .LBB0_195
	v_mul_f32_e32 v0, 0xbfb8aa3b, v138
	v_exp_f32_e32 v128, v0
	v_mul_f32_e32 v0, 0xbfb8aa3b, v139
	v_exp_f32_e32 v129, v0
	v_mul_f32_e32 v0, 0xbfb8aa3b, v136
	v_exp_f32_e32 v130, v0
	v_mul_f32_e32 v0, 0xbfb8aa3b, v137
	v_pk_add_f32 v[128:129], v[128:129], 1.0 op_sel_hi:[1,0]
	v_exp_f32_e32 v131, v0
	s_nop 0
	v_pk_add_f32 v[130:131], v[130:131], 1.0 op_sel_hi:[1,0]
	v_rcp_f32_e32 v127, v128
	s_nop 0
	v_mul_f32_e32 v128, v138, v127
	v_rcp_f32_e32 v127, v129
	s_nop 0
	v_mul_f32_e32 v129, v139, v127
	v_rcp_f32_e32 v127, v130
	s_nop 0
	v_mul_f32_e32 v130, v136, v127
	v_rcp_f32_e32 v127, v131
	s_nop 0
	v_mul_f32_e32 v131, v137, v127

; DI float siluf_(float x) { return x / (1.f + __expf(-x)); }
; template <int EPI>
; DI void gemm_tile(const GemmArgs& ga, const EpiArgs& ea, int m0, int n0, char* lds) {
;     ...
;           } else if (slot == 1 || slot == 5 || slot == 7 || slot == 9) {
; #pragma unroll
;             for (int r = 0; r < 4; ++r) v[r] = siluf_(v[r]);
.LBB0_214:
	s_and_b64 vcc, exec, s[44:45]
	s_cbranch_vccz .LBB0_216
	v_mul_f32_e32 v0, 0xbfb8aa3b, v142
	v_exp_f32_e32 v122, v0
	v_mul_f32_e32 v0, 0xbfb8aa3b, v143
	v_exp_f32_e32 v123, v0
	v_mul_f32_e32 v0, 0xbfb8aa3b, v140
	v_exp_f32_e32 v124, v0
	v_mul_f32_e32 v0, 0xbfb8aa3b, v141
	v_pk_add_f32 v[122:123], v[122:123], 1.0 op_sel_hi:[1,0]
	v_exp_f32_e32 v125, v0
	s_nop 0
	v_pk_add_f32 v[124:125], v[124:125], 1.0 op_sel_hi:[1,0]
	v_rcp_f32_e32 v129, v122
	s_nop 0
	v_mul_f32_e32 v122, v142, v129
	v_rcp_f32_e32 v129, v123
	s_nop 0
	v_mul_f32_e32 v123, v143, v129
	v_rcp_f32_e32 v129, v124
	s_nop 0
	v_mul_f32_e32 v124, v140, v129
	v_rcp_f32_e32 v129, v125
	s_nop 0
	v_mul_f32_e32 v125, v141, v129

; DI float siluf_(float x) { return x / (1.f + __expf(-x)); }
; template <int EPI>
; DI void gemm_tile(const GemmArgs& ga, const EpiArgs& ea, int m0, int n0, char* lds) {
;     ...
;           } else if (slot == 1 || slot == 5 || slot == 7 || slot == 9) {
; #pragma unroll
;             for (int r = 0; r < 4; ++r) v[r] = siluf_(v[r]);
.LBB0_236:
	s_and_b64 vcc, exec, s[44:45]
	s_cbranch_vccz .LBB0_238
	v_mul_f32_e32 v0, 0xbfb8aa3b, v160
	v_exp_f32_e32 v118, v0
	v_mul_f32_e32 v0, 0xbfb8aa3b, v161
	v_exp_f32_e32 v119, v0
	v_mul_f32_e32 v0, 0xbfb8aa3b, v158
	v_exp_f32_e32 v120, v0
	v_mul_f32_e32 v0, 0xbfb8aa3b, v159
	v_pk_add_f32 v[118:119], v[118:119], 1.0 op_sel_hi:[1,0]
	v_exp_f32_e32 v121, v0
	s_nop 0
	v_pk_add_f32 v[120:121], v[120:121], 1.0 op_sel_hi:[1,0]
	v_rcp_f32_e32 v123, v118
	s_nop 0
	v_mul_f32_e32 v118, v160, v123
	v_rcp_f32_e32 v123, v119
	s_nop 0
	v_mul_f32_e32 v119, v161, v123
	v_rcp_f32_e32 v123, v120
	s_nop 0
	v_mul_f32_e32 v120, v158, v123
	v_rcp_f32_e32 v123, v121
	s_nop 0
	v_mul_f32_e32 v121, v159, v123

; DI float siluf_(float x) { return x / (1.f + __expf(-x)); }
; template <int EPI>
; DI void gemm_tile(const GemmArgs& ga, const EpiArgs& ea, int m0, int n0, char* lds) {
;     ...
;           } else if (slot == 1 || slot == 5 || slot == 7 || slot == 9) {
; #pragma unroll
;             for (int r = 0; r < 4; ++r) v[r] = siluf_(v[r]);
.LBB0_258:
	s_and_b64 vcc, exec, s[44:45]
	s_cbranch_vccz .LBB0_260
	v_mul_f32_e32 v0, 0xbfb8aa3b, v160
	v_exp_f32_e32 v114, v0
	v_mul_f32_e32 v0, 0xbfb8aa3b, v161
	v_exp_f32_e32 v115, v0
	v_mul_f32_e32 v0, 0xbfb8aa3b, v158
	v_exp_f32_e32 v116, v0
	v_mul_f32_e32 v0, 0xbfb8aa3b, v159
	v_pk_add_f32 v[114:115], v[114:115], 1.0 op_sel_hi:[1,0]
	v_exp_f32_e32 v117, v0
	s_nop 0
	v_pk_add_f32 v[116:117], v[116:117], 1.0 op_sel_hi:[1,0]
	v_rcp_f32_e32 v119, v114
	s_nop 0
	v_mul_f32_e32 v114, v160, v119
	v_rcp_f32_e32 v119, v115
	s_nop 0
	v_mul_f32_e32 v115, v161, v119
	v_rcp_f32_e32 v119, v116
	s_nop 0
	v_mul_f32_e32 v116, v158, v119
	v_rcp_f32_e32 v119, v117
	s_nop 0
	v_mul_f32_e32 v117, v159, v119

; DI float siluf_(float x) { return x / (1.f + __expf(-x)); }
; template <int EPI>
; DI void gemm_tile(const GemmArgs& ga, const EpiArgs& ea, int m0, int n0, char* lds) {
;     ...
;           } else if (slot == 1 || slot == 5 || slot == 7 || slot == 9) {
; #pragma unroll
;             for (int r = 0; r < 4; ++r) v[r] = siluf_(v[r]);
.LBB0_280:
	s_and_b64 vcc, exec, s[44:45]
	s_cbranch_vccz .LBB0_282
	v_mul_f32_e32 v0, 0xbfb8aa3b, v160
	v_exp_f32_e32 v110, v0
	v_mul_f32_e32 v0, 0xbfb8aa3b, v161
	v_exp_f32_e32 v111, v0
	v_mul_f32_e32 v0, 0xbfb8aa3b, v112
	v_exp_f32_e32 v164, v0
	v_mul_f32_e32 v0, 0xbfb8aa3b, v113
	v_pk_add_f32 v[110:111], v[110:111], 1.0 op_sel_hi:[1,0]
	v_exp_f32_e32 v165, v0
	s_nop 0
	v_pk_add_f32 v[164:165], v[164:165], 1.0 op_sel_hi:[1,0]
	v_rcp_f32_e32 v115, v110
	s_nop 0
	v_mul_f32_e32 v110, v160, v115
	v_rcp_f32_e32 v115, v111
	s_nop 0
	v_mul_f32_e32 v111, v161, v115
	v_rcp_f32_e32 v115, v164
	s_nop 0
	v_mul_f32_e32 v164, v112, v115
	v_rcp_f32_e32 v115, v165
	s_nop 0
	v_mul_f32_e32 v165, v113, v115

; DI float siluf_(float x) { return x / (1.f + __expf(-x)); }
; template <int EPI>
; DI void gemm_tile(const GemmArgs& ga, const EpiArgs& ea, int m0, int n0, char* lds) {
;     ...
;           } else if (slot == 1 || slot == 5 || slot == 7 || slot == 9) {
; #pragma unroll
;             for (int r = 0; r < 4; ++r) v[r] = siluf_(v[r]);
.LBB0_301:
	s_and_b64 vcc, exec, s[44:45]
	s_cbranch_vccz .LBB0_303
	v_mul_f32_e32 v0, 0xbfb8aa3b, v112
	v_exp_f32_e32 v108, v0
	v_mul_f32_e32 v0, 0xbfb8aa3b, v113
	v_exp_f32_e32 v109, v0
	v_mul_f32_e32 v0, 0xbfb8aa3b, v106
	v_exp_f32_e32 v160, v0
	v_mul_f32_e32 v0, 0xbfb8aa3b, v107
	v_pk_add_f32 v[108:109], v[108:109], 1.0 op_sel_hi:[1,0]
	v_exp_f32_e32 v161, v0
	s_nop 0
	v_pk_add_f32 v[160:161], v[160:161], 1.0 op_sel_hi:[1,0]
	v_rcp_f32_e32 v111, v108
	s_nop 0
	v_mul_f32_e32 v108, v112, v111
	v_rcp_f32_e32 v111, v109
	s_nop 0
	v_mul_f32_e32 v109, v113, v111
	v_rcp_f32_e32 v111, v160
	s_nop 0
	v_mul_f32_e32 v160, v106, v111
	v_rcp_f32_e32 v111, v161
	s_nop 0
	v_mul_f32_e32 v161, v107, v111

; DI float siluf_(float x) { return x / (1.f + __expf(-x)); }
; template <int EPI>
; DI void gemm_tile(const GemmArgs& ga, const EpiArgs& ea, int m0, int n0, char* lds) {
;     ...
;           } else if (slot == 1 || slot == 5 || slot == 7 || slot == 9) {
; #pragma unroll
;             for (int r = 0; r < 4; ++r) v[r] = siluf_(v[r]);
.LBB0_323:
	s_and_b64 vcc, exec, s[44:45]
	s_cbranch_vccz .LBB0_325
	v_mul_f32_e32 v0, 0xbfb8aa3b, v106
	v_exp_f32_e32 v104, v0
	v_mul_f32_e32 v0, 0xbfb8aa3b, v107
	v_exp_f32_e32 v105, v0
	v_mul_f32_e32 v0, 0xbfb8aa3b, v102
	v_exp_f32_e32 v108, v0
	v_mul_f32_e32 v0, 0xbfb8aa3b, v103
	v_pk_add_f32 v[104:105], v[104:105], 1.0 op_sel_hi:[1,0]
	v_exp_f32_e32 v109, v0
	s_nop 0
	v_pk_add_f32 v[108:109], v[108:109], 1.0 op_sel_hi:[1,0]
	v_rcp_f32_e32 v111, v104
	s_nop 0
	v_mul_f32_e32 v104, v106, v111
	v_rcp_f32_e32 v111, v105
	s_nop 0
	v_mul_f32_e32 v105, v107, v111
	v_rcp_f32_e32 v111, v108
	s_nop 0
	v_mul_f32_e32 v108, v102, v111
	v_rcp_f32_e32 v111, v109
	s_nop 0
	v_mul_f32_e32 v109, v103, v111

; DI float siluf_(float x) { return x / (1.f + __expf(-x)); }
; template <int EPI>
; DI void gemm_tile(const GemmArgs& ga, const EpiArgs& ea, int m0, int n0, char* lds) {
;     ...
;           } else if (slot == 1 || slot == 5 || slot == 7 || slot == 9) {
; #pragma unroll
;             for (int r = 0; r < 4; ++r) v[r] = siluf_(v[r]);
.LBB0_345:
	s_and_b64 vcc, exec, s[44:45]
	s_cbranch_vccz .LBB0_347
	v_mul_f32_e32 v0, 0xbfb8aa3b, v102
	v_exp_f32_e32 v100, v0
	v_mul_f32_e32 v0, 0xbfb8aa3b, v103
	v_exp_f32_e32 v101, v0
	v_mul_f32_e32 v0, 0xbfb8aa3b, v98
	v_exp_f32_e32 v104, v0
	v_mul_f32_e32 v0, 0xbfb8aa3b, v99
	v_pk_add_f32 v[100:101], v[100:101], 1.0 op_sel_hi:[1,0]
	v_exp_f32_e32 v105, v0
	s_nop 0
	v_pk_add_f32 v[104:105], v[104:105], 1.0 op_sel_hi:[1,0]
	v_rcp_f32_e32 v106, v100
	s_nop 0
	v_mul_f32_e32 v100, v102, v106
	v_rcp_f32_e32 v106, v101
	s_nop 0
	v_mul_f32_e32 v101, v103, v106
	v_rcp_f32_e32 v106, v104
	s_nop 0
	v_mul_f32_e32 v104, v98, v106
	v_rcp_f32_e32 v106, v105
	s_nop 0
	v_mul_f32_e32 v105, v99, v106

; DI float siluf_(float x) { return x / (1.f + __expf(-x)); }
; template <int EPI>
; DI void gemm_tile(const GemmArgs& ga, const EpiArgs& ea, int m0, int n0, char* lds) {
;     ...
;           } else if (slot == 1 || slot == 5 || slot == 7 || slot == 9) {
; #pragma unroll
;             for (int r = 0; r < 4; ++r) v[r] = siluf_(v[r]);
.LBB0_367:
	s_and_b64 vcc, exec, s[44:45]
	s_cbranch_vccz .LBB0_369
	v_mul_f32_e32 v0, 0xbfb8aa3b, v102
	v_exp_f32_e32 v94, v0
	v_mul_f32_e32 v0, 0xbfb8aa3b, v103
	v_exp_f32_e32 v95, v0
	v_mul_f32_e32 v0, 0xbfb8aa3b, v96
	v_exp_f32_e32 v106, v0
	v_mul_f32_e32 v0, 0xbfb8aa3b, v97
	v_pk_add_f32 v[94:95], v[94:95], 1.0 op_sel_hi:[1,0]
	v_exp_f32_e32 v107, v0
	s_nop 0
	v_pk_add_f32 v[106:107], v[106:107], 1.0 op_sel_hi:[1,0]
	v_rcp_f32_e32 v101, v94
	s_nop 0
	v_mul_f32_e32 v94, v102, v101
	v_rcp_f32_e32 v101, v95
	s_nop 0
	v_mul_f32_e32 v95, v103, v101
	v_rcp_f32_e32 v101, v106
	s_nop 0
	v_mul_f32_e32 v106, v96, v101
	v_rcp_f32_e32 v101, v107
	s_nop 0
	v_mul_f32_e32 v107, v97, v101

; DI float siluf_(float x) { return x / (1.f + __expf(-x)); }
; template <int EPI>
; DI void gemm_tile(const GemmArgs& ga, const EpiArgs& ea, int m0, int n0, char* lds) {
;     ...
;           } else if (slot == 1 || slot == 5 || slot == 7 || slot == 9) {
; #pragma unroll
;             for (int r = 0; r < 4; ++r) v[r] = siluf_(v[r]);
.LBB0_388:
	s_and_b64 vcc, exec, s[44:45]
	s_cbranch_vccz .LBB0_390
	v_mul_f32_e32 v0, 0xbfb8aa3b, v96
	v_exp_f32_e32 v92, v0
	v_mul_f32_e32 v0, 0xbfb8aa3b, v97
	v_exp_f32_e32 v93, v0
	v_mul_f32_e32 v0, 0xbfb8aa3b, v90
	v_exp_f32_e32 v102, v0
	v_mul_f32_e32 v0, 0xbfb8aa3b, v91
	v_pk_add_f32 v[92:93], v[92:93], 1.0 op_sel_hi:[1,0]
	v_exp_f32_e32 v103, v0
	s_nop 0
	v_pk_add_f32 v[102:103], v[102:103], 1.0 op_sel_hi:[1,0]
	v_rcp_f32_e32 v95, v92
	s_nop 0
	v_mul_f32_e32 v92, v96, v95
	v_rcp_f32_e32 v95, v93
	s_nop 0
	v_mul_f32_e32 v93, v97, v95
	v_rcp_f32_e32 v95, v102
	s_nop 0
	v_mul_f32_e32 v102, v90, v95
	v_rcp_f32_e32 v95, v103
	s_nop 0
	v_mul_f32_e32 v103, v91, v95

; DI float siluf_(float x) { return x / (1.f + __expf(-x)); }
; template <int EPI>
; DI void gemm_tile(const GemmArgs& ga, const EpiArgs& ea, int m0, int n0, char* lds) {
;     ...
;           } else if (slot == 1 || slot == 5 || slot == 7 || slot == 9) {
; #pragma unroll
;             for (int r = 0; r < 4; ++r) v[r] = siluf_(v[r]);
.LBB0_410:
	s_and_b64 vcc, exec, s[44:45]
	s_cbranch_vccz .LBB0_412
	v_mul_f32_e32 v0, 0xbfb8aa3b, v90
	v_exp_f32_e32 v88, v0
	v_mul_f32_e32 v0, 0xbfb8aa3b, v91
	v_exp_f32_e32 v89, v0
	v_mul_f32_e32 v0, 0xbfb8aa3b, v86
	v_exp_f32_e32 v92, v0
	v_mul_f32_e32 v0, 0xbfb8aa3b, v87
	v_pk_add_f32 v[88:89], v[88:89], 1.0 op_sel_hi:[1,0]
	v_exp_f32_e32 v93, v0
	s_nop 0
	v_pk_add_f32 v[92:93], v[92:93], 1.0 op_sel_hi:[1,0]
	v_rcp_f32_e32 v95, v88
	s_nop 0
	v_mul_f32_e32 v88, v90, v95
	v_rcp_f32_e32 v95, v89
	s_nop 0
	v_mul_f32_e32 v89, v91, v95
	v_rcp_f32_e32 v95, v92
	s_nop 0
	v_mul_f32_e32 v92, v86, v95
	v_rcp_f32_e32 v95, v93
	s_nop 0
	v_mul_f32_e32 v93, v87, v95

; DI float siluf_(float x) { return x / (1.f + __expf(-x)); }
; template <int EPI>
; DI void gemm_tile(const GemmArgs& ga, const EpiArgs& ea, int m0, int n0, char* lds) {
;     ...
;           } else if (slot == 1 || slot == 5 || slot == 7 || slot == 9) {
; #pragma unroll
;             for (int r = 0; r < 4; ++r) v[r] = siluf_(v[r]);
.LBB0_432:
	s_and_b64 vcc, exec, s[44:45]
	s_cbranch_vccz .LBB0_434
	v_mul_f32_e32 v0, 0xbfb8aa3b, v86
	v_exp_f32_e32 v84, v0
	v_mul_f32_e32 v0, 0xbfb8aa3b, v87
	v_exp_f32_e32 v85, v0
	v_mul_f32_e32 v0, 0xbfb8aa3b, v82
	v_exp_f32_e32 v88, v0
	v_mul_f32_e32 v0, 0xbfb8aa3b, v83
	v_pk_add_f32 v[84:85], v[84:85], 1.0 op_sel_hi:[1,0]
	v_exp_f32_e32 v89, v0
	s_nop 0
	v_pk_add_f32 v[88:89], v[88:89], 1.0 op_sel_hi:[1,0]
	v_rcp_f32_e32 v90, v84
	s_nop 0
	v_mul_f32_e32 v84, v86, v90
	v_rcp_f32_e32 v90, v85
	s_nop 0
	v_mul_f32_e32 v85, v87, v90
	v_rcp_f32_e32 v90, v88
	s_nop 0
	v_mul_f32_e32 v88, v82, v90
	v_rcp_f32_e32 v90, v89
	s_nop 0
	v_mul_f32_e32 v89, v83, v90

; DI float siluf_(float x) { return x / (1.f + __expf(-x)); }
; template <int EPI>
; DI void gemm_tile(const GemmArgs& ga, const EpiArgs& ea, int m0, int n0, char* lds) {
;     ...
;           } else if (slot == 1 || slot == 5 || slot == 7 || slot == 9) {
; #pragma unroll
;             for (int r = 0; r < 4; ++r) v[r] = siluf_(v[r]);
.LBB0_454:
	s_and_b64 vcc, exec, s[44:45]
	s_cbranch_vccz .LBB0_456
	v_mul_f32_e32 v0, 0xbfb8aa3b, v86
	v_exp_f32_e32 v78, v0
	v_mul_f32_e32 v0, 0xbfb8aa3b, v87
	v_exp_f32_e32 v79, v0
	v_mul_f32_e32 v0, 0xbfb8aa3b, v80
	v_exp_f32_e32 v90, v0
	v_mul_f32_e32 v0, 0xbfb8aa3b, v81
	v_pk_add_f32 v[78:79], v[78:79], 1.0 op_sel_hi:[1,0]
	v_exp_f32_e32 v91, v0
	s_nop 0
	v_pk_add_f32 v[90:91], v[90:91], 1.0 op_sel_hi:[1,0]
	v_rcp_f32_e32 v85, v78
	s_nop 0
	v_mul_f32_e32 v78, v86, v85
	v_rcp_f32_e32 v85, v79
	s_nop 0
	v_mul_f32_e32 v79, v87, v85
	v_rcp_f32_e32 v85, v90
	s_nop 0
	v_mul_f32_e32 v90, v80, v85
	v_rcp_f32_e32 v85, v91
	s_nop 0
	v_mul_f32_e32 v91, v81, v85

; DI float siluf_(float x) { return x / (1.f + __expf(-x)); }
; template <int EPI>
; DI void gemm_tile(const GemmArgs& ga, const EpiArgs& ea, int m0, int n0, char* lds) {
;     ...
;           } else if (slot == 1 || slot == 5 || slot == 7 || slot == 9) {
; #pragma unroll
;             for (int r = 0; r < 4; ++r) v[r] = siluf_(v[r]);
.LBB0_475:
	s_and_b64 vcc, exec, s[44:45]
	s_cbranch_vccz .LBB0_477
	v_mul_f32_e32 v0, 0xbfb8aa3b, v80
	v_exp_f32_e32 v76, v0
	v_mul_f32_e32 v0, 0xbfb8aa3b, v81
	v_exp_f32_e32 v77, v0
	v_mul_f32_e32 v0, 0xbfb8aa3b, v74
	v_exp_f32_e32 v86, v0
	v_mul_f32_e32 v0, 0xbfb8aa3b, v75
	v_pk_add_f32 v[76:77], v[76:77], 1.0 op_sel_hi:[1,0]
	v_exp_f32_e32 v87, v0
	s_nop 0
	v_pk_add_f32 v[86:87], v[86:87], 1.0 op_sel_hi:[1,0]
	v_rcp_f32_e32 v79, v76
	s_nop 0
	v_mul_f32_e32 v76, v80, v79
	v_rcp_f32_e32 v79, v77
	s_nop 0
	v_mul_f32_e32 v77, v81, v79
	v_rcp_f32_e32 v79, v86
	s_nop 0
	v_mul_f32_e32 v86, v74, v79
	v_rcp_f32_e32 v79, v87
	s_nop 0
	v_mul_f32_e32 v87, v75, v79

; DI float siluf_(float x) { return x / (1.f + __expf(-x)); }
; template <int EPI>
; DI void gemm_tile(const GemmArgs& ga, const EpiArgs& ea, int m0, int n0, char* lds) {
;     ...
;           } else if (slot == 1 || slot == 5 || slot == 7 || slot == 9) {
; #pragma unroll
;             for (int r = 0; r < 4; ++r) v[r] = siluf_(v[r]);
.LBB0_497:
	s_and_b64 vcc, exec, s[44:45]
	s_cbranch_vccz .LBB0_499
	v_mul_f32_e32 v0, 0xbfb8aa3b, v74
	v_exp_f32_e32 v72, v0
	v_mul_f32_e32 v0, 0xbfb8aa3b, v75
	v_exp_f32_e32 v73, v0
	v_mul_f32_e32 v0, 0xbfb8aa3b, v70
	v_exp_f32_e32 v76, v0
	v_mul_f32_e32 v0, 0xbfb8aa3b, v71
	v_pk_add_f32 v[72:73], v[72:73], 1.0 op_sel_hi:[1,0]
	v_exp_f32_e32 v77, v0
	s_nop 0
	v_pk_add_f32 v[76:77], v[76:77], 1.0 op_sel_hi:[1,0]
	v_rcp_f32_e32 v79, v72
	s_nop 0
	v_mul_f32_e32 v72, v74, v79
	v_rcp_f32_e32 v79, v73
	s_nop 0
	v_mul_f32_e32 v73, v75, v79
	v_rcp_f32_e32 v79, v76
	s_nop 0
	v_mul_f32_e32 v76, v70, v79
	v_rcp_f32_e32 v79, v77
	s_nop 0
	v_mul_f32_e32 v77, v71, v79

; DI float siluf_(float x) { return x / (1.f + __expf(-x)); }
; template <int EPI>
; DI void gemm_tile(const GemmArgs& ga, const EpiArgs& ea, int m0, int n0, char* lds) {
;     ...
;           } else if (slot == 1 || slot == 5 || slot == 7 || slot == 9) {
; #pragma unroll
;             for (int r = 0; r < 4; ++r) v[r] = siluf_(v[r]);
.LBB0_519:
	s_and_b64 vcc, exec, s[44:45]
	s_cbranch_vccz .LBB0_521
	v_mul_f32_e32 v0, 0xbfb8aa3b, v70
	v_exp_f32_e32 v68, v0
	v_mul_f32_e32 v0, 0xbfb8aa3b, v71
	v_exp_f32_e32 v69, v0
	v_mul_f32_e32 v0, 0xbfb8aa3b, v66
	v_exp_f32_e32 v72, v0
	v_mul_f32_e32 v0, 0xbfb8aa3b, v67
	v_pk_add_f32 v[68:69], v[68:69], 1.0 op_sel_hi:[1,0]
	v_exp_f32_e32 v73, v0
	s_nop 0
	v_pk_add_f32 v[72:73], v[72:73], 1.0 op_sel_hi:[1,0]
	v_rcp_f32_e32 v74, v68
	s_nop 0
	v_mul_f32_e32 v68, v70, v74
	v_rcp_f32_e32 v74, v69
	s_nop 0
	v_mul_f32_e32 v69, v71, v74
	v_rcp_f32_e32 v74, v72
	s_nop 0
	v_mul_f32_e32 v72, v66, v74
	v_rcp_f32_e32 v74, v73
	s_nop 0
	v_mul_f32_e32 v73, v67, v74

; DI float siluf_(float x) { return x / (1.f + __expf(-x)); }
; template <int EPI>
; DI void gemm_tile(const GemmArgs& ga, const EpiArgs& ea, int m0, int n0, char* lds) {
;     ...
;           } else if (slot == 1 || slot == 5 || slot == 7 || slot == 9) {
; #pragma unroll
;             for (int r = 0; r < 4; ++r) v[r] = siluf_(v[r]);
.LBB0_541:
	s_and_b64 vcc, exec, s[44:45]
	s_cbranch_vccz .LBB0_543
	v_mul_f32_e32 v0, 0xbfb8aa3b, v70
	v_exp_f32_e32 v62, v0
	v_mul_f32_e32 v0, 0xbfb8aa3b, v71
	v_exp_f32_e32 v63, v0
	v_mul_f32_e32 v0, 0xbfb8aa3b, v64
	v_exp_f32_e32 v74, v0
	v_mul_f32_e32 v0, 0xbfb8aa3b, v65
	v_pk_add_f32 v[62:63], v[62:63], 1.0 op_sel_hi:[1,0]
	v_exp_f32_e32 v75, v0
	s_nop 0
	v_pk_add_f32 v[74:75], v[74:75], 1.0 op_sel_hi:[1,0]
	v_rcp_f32_e32 v69, v62
	s_nop 0
	v_mul_f32_e32 v62, v70, v69
	v_rcp_f32_e32 v69, v63
	s_nop 0
	v_mul_f32_e32 v63, v71, v69
	v_rcp_f32_e32 v69, v74
	s_nop 0
	v_mul_f32_e32 v74, v64, v69
	v_rcp_f32_e32 v69, v75
	s_nop 0
	v_mul_f32_e32 v75, v65, v69

; DI float siluf_(float x) { return x / (1.f + __expf(-x)); }
; template <int EPI>
; DI void gemm_tile(const GemmArgs& ga, const EpiArgs& ea, int m0, int n0, char* lds) {
;     ...
;           } else if (slot == 1 || slot == 5 || slot == 7 || slot == 9) {
; #pragma unroll
;             for (int r = 0; r < 4; ++r) v[r] = siluf_(v[r]);
.LBB0_562:
	s_and_b64 vcc, exec, s[44:45]
	s_cbranch_vccz .LBB0_564
	v_mul_f32_e32 v0, 0xbfb8aa3b, v64
	v_exp_f32_e32 v60, v0
	v_mul_f32_e32 v0, 0xbfb8aa3b, v65
	v_exp_f32_e32 v61, v0
	v_mul_f32_e32 v0, 0xbfb8aa3b, v58
	v_exp_f32_e32 v70, v0
	v_mul_f32_e32 v0, 0xbfb8aa3b, v59
	v_pk_add_f32 v[60:61], v[60:61], 1.0 op_sel_hi:[1,0]
	v_exp_f32_e32 v71, v0
	s_nop 0
	v_pk_add_f32 v[70:71], v[70:71], 1.0 op_sel_hi:[1,0]
	v_rcp_f32_e32 v63, v60
	s_nop 0
	v_mul_f32_e32 v60, v64, v63
	v_rcp_f32_e32 v63, v61
	s_nop 0
	v_mul_f32_e32 v61, v65, v63
	v_rcp_f32_e32 v63, v70
	s_nop 0
	v_mul_f32_e32 v70, v58, v63
	v_rcp_f32_e32 v63, v71
	s_nop 0
	v_mul_f32_e32 v71, v59, v63

; DI float siluf_(float x) { return x / (1.f + __expf(-x)); }
; template <int EPI>
; DI void gemm_tile(const GemmArgs& ga, const EpiArgs& ea, int m0, int n0, char* lds) {
;     ...
;           } else if (slot == 1 || slot == 5 || slot == 7 || slot == 9) {
; #pragma unroll
;             for (int r = 0; r < 4; ++r) v[r] = siluf_(v[r]);
.LBB0_584:
	s_and_b64 vcc, exec, s[44:45]
	s_cbranch_vccz .LBB0_586
	v_mul_f32_e32 v0, 0xbfb8aa3b, v58
	v_exp_f32_e32 v56, v0
	v_mul_f32_e32 v0, 0xbfb8aa3b, v59
	v_exp_f32_e32 v57, v0
	v_mul_f32_e32 v0, 0xbfb8aa3b, v54
	v_exp_f32_e32 v60, v0
	v_mul_f32_e32 v0, 0xbfb8aa3b, v55
	v_pk_add_f32 v[56:57], v[56:57], 1.0 op_sel_hi:[1,0]
	v_exp_f32_e32 v61, v0
	s_nop 0
	v_pk_add_f32 v[60:61], v[60:61], 1.0 op_sel_hi:[1,0]
	v_rcp_f32_e32 v63, v56
	s_nop 0
	v_mul_f32_e32 v56, v58, v63
	v_rcp_f32_e32 v63, v57
	s_nop 0
	v_mul_f32_e32 v57, v59, v63
	v_rcp_f32_e32 v63, v60
	s_nop 0
	v_mul_f32_e32 v60, v54, v63
	v_rcp_f32_e32 v63, v61
	s_nop 0
	v_mul_f32_e32 v61, v55, v63

; DI float siluf_(float x) { return x / (1.f + __expf(-x)); }
; template <int EPI>
; DI void gemm_tile(const GemmArgs& ga, const EpiArgs& ea, int m0, int n0, char* lds) {
;     ...
;           } else if (slot == 1 || slot == 5 || slot == 7 || slot == 9) {
; #pragma unroll
;             for (int r = 0; r < 4; ++r) v[r] = siluf_(v[r]);
.LBB0_606:
	s_and_b64 vcc, exec, s[44:45]
	s_cbranch_vccz .LBB0_608
	v_mul_f32_e32 v0, 0xbfb8aa3b, v54
	v_exp_f32_e32 v52, v0
	v_mul_f32_e32 v0, 0xbfb8aa3b, v55
	v_exp_f32_e32 v53, v0
	v_mul_f32_e32 v0, 0xbfb8aa3b, v50
	v_exp_f32_e32 v56, v0
	v_mul_f32_e32 v0, 0xbfb8aa3b, v51
	v_pk_add_f32 v[52:53], v[52:53], 1.0 op_sel_hi:[1,0]
	v_exp_f32_e32 v57, v0
	s_nop 0
	v_pk_add_f32 v[56:57], v[56:57], 1.0 op_sel_hi:[1,0]
	v_rcp_f32_e32 v58, v52
	s_nop 0
	v_mul_f32_e32 v52, v54, v58
	v_rcp_f32_e32 v58, v53
	s_nop 0
	v_mul_f32_e32 v53, v55, v58
	v_rcp_f32_e32 v58, v56
	s_nop 0
	v_mul_f32_e32 v56, v50, v58
	v_rcp_f32_e32 v58, v57
	s_nop 0
	v_mul_f32_e32 v57, v51, v58

; DI float siluf_(float x) { return x / (1.f + __expf(-x)); }
; template <int EPI>
; DI void gemm_tile(const GemmArgs& ga, const EpiArgs& ea, int m0, int n0, char* lds) {
;     ...
;           } else if (slot == 1 || slot == 5 || slot == 7 || slot == 9) {
; #pragma unroll
;             for (int r = 0; r < 4; ++r) v[r] = siluf_(v[r]);
.LBB0_628:
	s_and_b64 vcc, exec, s[44:45]
	s_cbranch_vccz .LBB0_630
	v_mul_f32_e32 v0, 0xbfb8aa3b, v54
	v_exp_f32_e32 v46, v0
	v_mul_f32_e32 v0, 0xbfb8aa3b, v55
	v_exp_f32_e32 v47, v0
	v_mul_f32_e32 v0, 0xbfb8aa3b, v48
	v_exp_f32_e32 v58, v0
	v_mul_f32_e32 v0, 0xbfb8aa3b, v49
	v_pk_add_f32 v[46:47], v[46:47], 1.0 op_sel_hi:[1,0]
	v_exp_f32_e32 v59, v0
	s_nop 0
	v_pk_add_f32 v[58:59], v[58:59], 1.0 op_sel_hi:[1,0]
	v_rcp_f32_e32 v53, v46
	s_nop 0
	v_mul_f32_e32 v46, v54, v53
	v_rcp_f32_e32 v53, v47
	s_nop 0
	v_mul_f32_e32 v47, v55, v53
	v_rcp_f32_e32 v53, v58
	s_nop 0
	v_mul_f32_e32 v58, v48, v53
	v_rcp_f32_e32 v53, v59
	s_nop 0
	v_mul_f32_e32 v59, v49, v53

; DI float siluf_(float x) { return x / (1.f + __expf(-x)); }
; template <int EPI>
; DI void gemm_tile(const GemmArgs& ga, const EpiArgs& ea, int m0, int n0, char* lds) {
;     ...
;           } else if (slot == 1 || slot == 5 || slot == 7 || slot == 9) {
; #pragma unroll
;             for (int r = 0; r < 4; ++r) v[r] = siluf_(v[r]);
.LBB0_649:
	s_and_b64 vcc, exec, s[44:45]
	s_cbranch_vccz .LBB0_651
	v_mul_f32_e32 v0, 0xbfb8aa3b, v48
	v_exp_f32_e32 v44, v0
	v_mul_f32_e32 v0, 0xbfb8aa3b, v49
	v_exp_f32_e32 v45, v0
	v_mul_f32_e32 v0, 0xbfb8aa3b, v42
	v_exp_f32_e32 v54, v0
	v_mul_f32_e32 v0, 0xbfb8aa3b, v43
	v_pk_add_f32 v[44:45], v[44:45], 1.0 op_sel_hi:[1,0]
	v_exp_f32_e32 v55, v0
	s_nop 0
	v_pk_add_f32 v[54:55], v[54:55], 1.0 op_sel_hi:[1,0]
	v_rcp_f32_e32 v47, v44
	s_nop 0
	v_mul_f32_e32 v44, v48, v47
	v_rcp_f32_e32 v47, v45
	s_nop 0
	v_mul_f32_e32 v45, v49, v47
	v_rcp_f32_e32 v47, v54
	s_nop 0
	v_mul_f32_e32 v54, v42, v47
	v_rcp_f32_e32 v47, v55
	s_nop 0
	v_mul_f32_e32 v55, v43, v47

; DI float siluf_(float x) { return x / (1.f + __expf(-x)); }
; template <int EPI>
; DI void gemm_tile(const GemmArgs& ga, const EpiArgs& ea, int m0, int n0, char* lds) {
;     ...
;           } else if (slot == 1 || slot == 5 || slot == 7 || slot == 9) {
; #pragma unroll
;             for (int r = 0; r < 4; ++r) v[r] = siluf_(v[r]);
.LBB0_671:
	s_and_b64 vcc, exec, s[44:45]
	s_cbranch_vccz .LBB0_673
	v_mul_f32_e32 v0, 0xbfb8aa3b, v42
	v_exp_f32_e32 v40, v0
	v_mul_f32_e32 v0, 0xbfb8aa3b, v43
	v_exp_f32_e32 v41, v0
	v_mul_f32_e32 v0, 0xbfb8aa3b, v38
	v_exp_f32_e32 v44, v0
	v_mul_f32_e32 v0, 0xbfb8aa3b, v39
	v_pk_add_f32 v[40:41], v[40:41], 1.0 op_sel_hi:[1,0]
	v_exp_f32_e32 v45, v0
	s_nop 0
	v_pk_add_f32 v[44:45], v[44:45], 1.0 op_sel_hi:[1,0]
	v_rcp_f32_e32 v47, v40
	s_nop 0
	v_mul_f32_e32 v40, v42, v47
	v_rcp_f32_e32 v47, v41
	s_nop 0
	v_mul_f32_e32 v41, v43, v47
	v_rcp_f32_e32 v47, v44
	s_nop 0
	v_mul_f32_e32 v44, v38, v47
	v_rcp_f32_e32 v47, v45
	s_nop 0
	v_mul_f32_e32 v45, v39, v47

; DI float siluf_(float x) { return x / (1.f + __expf(-x)); }
; template <int EPI>
; DI void gemm_tile(const GemmArgs& ga, const EpiArgs& ea, int m0, int n0, char* lds) {
;     ...
;           } else if (slot == 1 || slot == 5 || slot == 7 || slot == 9) {
; #pragma unroll
;             for (int r = 0; r < 4; ++r) v[r] = siluf_(v[r]);
.LBB0_693:
	s_and_b64 vcc, exec, s[44:45]
	s_cbranch_vccz .LBB0_695
	v_mul_f32_e32 v0, 0xbfb8aa3b, v38
	v_exp_f32_e32 v36, v0
	v_mul_f32_e32 v0, 0xbfb8aa3b, v39
	v_exp_f32_e32 v37, v0
	v_mul_f32_e32 v0, 0xbfb8aa3b, v34
	v_exp_f32_e32 v40, v0
	v_mul_f32_e32 v0, 0xbfb8aa3b, v35
	v_pk_add_f32 v[36:37], v[36:37], 1.0 op_sel_hi:[1,0]
	v_exp_f32_e32 v41, v0
	s_nop 0
	v_pk_add_f32 v[40:41], v[40:41], 1.0 op_sel_hi:[1,0]
	v_rcp_f32_e32 v42, v36
	s_nop 0
	v_mul_f32_e32 v36, v38, v42
	v_rcp_f32_e32 v42, v37
	s_nop 0
	v_mul_f32_e32 v37, v39, v42
	v_rcp_f32_e32 v42, v40
	s_nop 0
	v_mul_f32_e32 v40, v34, v42
	v_rcp_f32_e32 v42, v41
	s_nop 0
	v_mul_f32_e32 v41, v35, v42

; DI float siluf_(float x) { return x / (1.f + __expf(-x)); }
; template <int EPI>
; DI void gemm_tile(const GemmArgs& ga, const EpiArgs& ea, int m0, int n0, char* lds) {
;     ...
;           } else if (slot == 1 || slot == 5 || slot == 7 || slot == 9) {
; #pragma unroll
;             for (int r = 0; r < 4; ++r) v[r] = siluf_(v[r]);
.LBB0_715:
	s_and_b64 vcc, exec, s[44:45]
	s_cbranch_vccz .LBB0_717
	v_mul_f32_e32 v0, 0xbfb8aa3b, v38
	v_exp_f32_e32 v30, v0
	v_mul_f32_e32 v0, 0xbfb8aa3b, v39
	v_exp_f32_e32 v31, v0
	v_mul_f32_e32 v0, 0xbfb8aa3b, v32
	v_exp_f32_e32 v42, v0
	v_mul_f32_e32 v0, 0xbfb8aa3b, v33
	v_pk_add_f32 v[30:31], v[30:31], 1.0 op_sel_hi:[1,0]
	v_exp_f32_e32 v43, v0
	s_nop 0
	v_pk_add_f32 v[42:43], v[42:43], 1.0 op_sel_hi:[1,0]
	v_rcp_f32_e32 v37, v30
	s_nop 0
	v_mul_f32_e32 v30, v38, v37
	v_rcp_f32_e32 v37, v31
	s_nop 0
	v_mul_f32_e32 v31, v39, v37
	v_rcp_f32_e32 v37, v42
	s_nop 0
	v_mul_f32_e32 v42, v32, v37
	v_rcp_f32_e32 v37, v43
	s_nop 0
	v_mul_f32_e32 v43, v33, v37

; DI float siluf_(float x) { return x / (1.f + __expf(-x)); }
; template <int EPI>
; DI void gemm_tile(const GemmArgs& ga, const EpiArgs& ea, int m0, int n0, char* lds) {
;     ...
;           } else if (slot == 1 || slot == 5 || slot == 7 || slot == 9) {
; #pragma unroll
;             for (int r = 0; r < 4; ++r) v[r] = siluf_(v[r]);
.LBB0_736:
	s_and_b64 vcc, exec, s[44:45]
	s_cbranch_vccz .LBB0_738
	v_mul_f32_e32 v0, 0xbfb8aa3b, v32
	v_exp_f32_e32 v28, v0
	v_mul_f32_e32 v0, 0xbfb8aa3b, v33
	v_exp_f32_e32 v29, v0
	v_mul_f32_e32 v0, 0xbfb8aa3b, v26
	v_exp_f32_e32 v38, v0
	v_mul_f32_e32 v0, 0xbfb8aa3b, v27
	v_pk_add_f32 v[28:29], v[28:29], 1.0 op_sel_hi:[1,0]
	v_exp_f32_e32 v39, v0
	s_nop 0
	v_pk_add_f32 v[38:39], v[38:39], 1.0 op_sel_hi:[1,0]
	v_rcp_f32_e32 v31, v28
	s_nop 0
	v_mul_f32_e32 v28, v32, v31
	v_rcp_f32_e32 v31, v29
	s_nop 0
	v_mul_f32_e32 v29, v33, v31
	v_rcp_f32_e32 v31, v38
	s_nop 0
	v_mul_f32_e32 v38, v26, v31
	v_rcp_f32_e32 v31, v39
	s_nop 0
	v_mul_f32_e32 v39, v27, v31

; DI float siluf_(float x) { return x / (1.f + __expf(-x)); }
; template <int EPI>
; DI void gemm_tile(const GemmArgs& ga, const EpiArgs& ea, int m0, int n0, char* lds) {
;     ...
;           } else if (slot == 1 || slot == 5 || slot == 7 || slot == 9) {
; #pragma unroll
;             for (int r = 0; r < 4; ++r) v[r] = siluf_(v[r]);
.LBB0_758:
	s_and_b64 vcc, exec, s[44:45]
	s_cbranch_vccz .LBB0_760
	v_mul_f32_e32 v0, 0xbfb8aa3b, v26
	v_exp_f32_e32 v24, v0
	v_mul_f32_e32 v0, 0xbfb8aa3b, v27
	v_exp_f32_e32 v25, v0
	v_mul_f32_e32 v0, 0xbfb8aa3b, v22
	v_exp_f32_e32 v28, v0
	v_mul_f32_e32 v0, 0xbfb8aa3b, v23
	v_pk_add_f32 v[24:25], v[24:25], 1.0 op_sel_hi:[1,0]
	v_exp_f32_e32 v29, v0
	s_nop 0
	v_pk_add_f32 v[28:29], v[28:29], 1.0 op_sel_hi:[1,0]
	v_rcp_f32_e32 v31, v24
	s_nop 0
	v_mul_f32_e32 v24, v26, v31
	v_rcp_f32_e32 v31, v25
	s_nop 0
	v_mul_f32_e32 v25, v27, v31
	v_rcp_f32_e32 v31, v28
	s_nop 0
	v_mul_f32_e32 v28, v22, v31
	v_rcp_f32_e32 v31, v29
	s_nop 0
	v_mul_f32_e32 v29, v23, v31

; DI float siluf_(float x) { return x / (1.f + __expf(-x)); }
; template <int EPI>
; DI void gemm_tile(const GemmArgs& ga, const EpiArgs& ea, int m0, int n0, char* lds) {
;     ...
;           } else if (slot == 1 || slot == 5 || slot == 7 || slot == 9) {
; #pragma unroll
;             for (int r = 0; r < 4; ++r) v[r] = siluf_(v[r]);
.LBB0_780:
	s_and_b64 vcc, exec, s[44:45]
	s_cbranch_vccz .LBB0_782
	v_mul_f32_e32 v0, 0xbfb8aa3b, v22
	v_exp_f32_e32 v20, v0
	v_mul_f32_e32 v0, 0xbfb8aa3b, v23
	v_exp_f32_e32 v21, v0
	v_mul_f32_e32 v0, 0xbfb8aa3b, v18
	v_exp_f32_e32 v24, v0
	v_mul_f32_e32 v0, 0xbfb8aa3b, v19
	v_pk_add_f32 v[20:21], v[20:21], 1.0 op_sel_hi:[1,0]
	v_exp_f32_e32 v25, v0
	s_nop 0
	v_pk_add_f32 v[24:25], v[24:25], 1.0 op_sel_hi:[1,0]
	v_rcp_f32_e32 v26, v20
	s_nop 0
	v_mul_f32_e32 v20, v22, v26
	v_rcp_f32_e32 v26, v21
	s_nop 0
	v_mul_f32_e32 v21, v23, v26
	v_rcp_f32_e32 v26, v24
	s_nop 0
	v_mul_f32_e32 v24, v18, v26
	v_rcp_f32_e32 v26, v25
	s_nop 0
	v_mul_f32_e32 v25, v19, v26

; DI float siluf_(float x) { return x / (1.f + __expf(-x)); }
; template <int EPI>
; DI void gemm_tile(const GemmArgs& ga, const EpiArgs& ea, int m0, int n0, char* lds) {
;     ...
;           } else if (slot == 1 || slot == 5 || slot == 7 || slot == 9) {
; #pragma unroll
;             for (int r = 0; r < 4; ++r) v[r] = siluf_(v[r]);
.LBB0_802:
	s_and_b64 vcc, exec, s[44:45]
	s_cbranch_vccz .LBB0_804
	v_mul_f32_e32 v0, 0xbfb8aa3b, v22
	v_exp_f32_e32 v14, v0
	v_mul_f32_e32 v0, 0xbfb8aa3b, v23
	v_exp_f32_e32 v15, v0
	v_mul_f32_e32 v0, 0xbfb8aa3b, v16
	v_exp_f32_e32 v26, v0
	v_mul_f32_e32 v0, 0xbfb8aa3b, v17
	v_pk_add_f32 v[14:15], v[14:15], 1.0 op_sel_hi:[1,0]
	v_exp_f32_e32 v27, v0
	s_nop 0
	v_pk_add_f32 v[26:27], v[26:27], 1.0 op_sel_hi:[1,0]
	v_rcp_f32_e32 v21, v14
	s_nop 0
	v_mul_f32_e32 v14, v22, v21
	v_rcp_f32_e32 v21, v15
	s_nop 0
	v_mul_f32_e32 v15, v23, v21
	v_rcp_f32_e32 v21, v26
	s_nop 0
	v_mul_f32_e32 v26, v16, v21
	v_rcp_f32_e32 v21, v27
	s_nop 0
	v_mul_f32_e32 v27, v17, v21

; DI float siluf_(float x) { return x / (1.f + __expf(-x)); }
; template <int EPI>
; DI void gemm_tile(const GemmArgs& ga, const EpiArgs& ea, int m0, int n0, char* lds) {
;     ...
;           } else if (slot == 1 || slot == 5 || slot == 7 || slot == 9) {
; #pragma unroll
;             for (int r = 0; r < 4; ++r) v[r] = siluf_(v[r]);
.LBB0_823:
	s_and_b64 vcc, exec, s[40:41]
	s_cbranch_vccz .LBB0_825
	v_mul_f32_e32 v0, 0xbfb8aa3b, v16
	v_exp_f32_e32 v12, v0
	v_mul_f32_e32 v0, 0xbfb8aa3b, v17
	v_exp_f32_e32 v13, v0
	v_mul_f32_e32 v0, 0xbfb8aa3b, v10
	v_exp_f32_e32 v22, v0
	v_mul_f32_e32 v0, 0xbfb8aa3b, v11
	v_pk_add_f32 v[12:13], v[12:13], 1.0 op_sel_hi:[1,0]
	v_exp_f32_e32 v23, v0
	s_nop 0
	v_pk_add_f32 v[22:23], v[22:23], 1.0 op_sel_hi:[1,0]
	v_rcp_f32_e32 v15, v12
	s_nop 0
	v_mul_f32_e32 v12, v16, v15
	v_rcp_f32_e32 v15, v13
	s_nop 0
	v_mul_f32_e32 v13, v17, v15
	v_rcp_f32_e32 v15, v22
	s_nop 0
	v_mul_f32_e32 v22, v10, v15
	v_rcp_f32_e32 v15, v23
	s_nop 0
	v_mul_f32_e32 v23, v11, v15

; DI float siluf_(float x) { return x / (1.f + __expf(-x)); }
; template <int EPI>
; DI void gemm_tile(const GemmArgs& ga, const EpiArgs& ea, int m0, int n0, char* lds) {
;     ...
;           } else if (slot == 1 || slot == 5 || slot == 7 || slot == 9) {
; #pragma unroll
;             for (int r = 0; r < 4; ++r) v[r] = siluf_(v[r]);
.LBB0_845:
	s_and_b64 vcc, exec, s[40:41]
	s_cbranch_vccz .LBB0_847
	v_mul_f32_e32 v0, 0xbfb8aa3b, v10
	v_exp_f32_e32 v8, v0
	v_mul_f32_e32 v0, 0xbfb8aa3b, v11
	v_exp_f32_e32 v9, v0
	v_mul_f32_e32 v0, 0xbfb8aa3b, v6
	v_exp_f32_e32 v12, v0
	v_mul_f32_e32 v0, 0xbfb8aa3b, v7
	v_pk_add_f32 v[8:9], v[8:9], 1.0 op_sel_hi:[1,0]
	v_exp_f32_e32 v13, v0
	s_nop 0
	v_pk_add_f32 v[12:13], v[12:13], 1.0 op_sel_hi:[1,0]
	v_rcp_f32_e32 v15, v8
	s_nop 0
	v_mul_f32_e32 v8, v10, v15
	v_rcp_f32_e32 v15, v9
	s_nop 0
	v_mul_f32_e32 v9, v11, v15
	v_rcp_f32_e32 v15, v12
	s_nop 0
	v_mul_f32_e32 v12, v6, v15
	v_rcp_f32_e32 v15, v13
	s_nop 0
	v_mul_f32_e32 v13, v7, v15

; DI float siluf_(float x) { return x / (1.f + __expf(-x)); }
; template <int EPI>
; DI void gemm_tile(const GemmArgs& ga, const EpiArgs& ea, int m0, int n0, char* lds) {
;     ...
;           } else if (slot == 1 || slot == 5 || slot == 7 || slot == 9) {
; #pragma unroll
;             for (int r = 0; r < 4; ++r) v[r] = siluf_(v[r]);
.LBB0_867:
	s_and_b64 vcc, exec, s[26:27]
	s_cbranch_vccz .LBB0_869
	v_mul_f32_e32 v0, 0xbfb8aa3b, v6
	v_exp_f32_e32 v4, v0
	v_mul_f32_e32 v0, 0xbfb8aa3b, v7
	v_exp_f32_e32 v5, v0
	v_mul_f32_e32 v0, 0xbfb8aa3b, v2
	v_exp_f32_e32 v8, v0
	v_mul_f32_e32 v0, 0xbfb8aa3b, v3
	v_pk_add_f32 v[4:5], v[4:5], 1.0 op_sel_hi:[1,0]
	v_exp_f32_e32 v9, v0
	s_nop 0
	v_pk_add_f32 v[8:9], v[8:9], 1.0 op_sel_hi:[1,0]
	v_rcp_f32_e32 v10, v4
	s_nop 0
	v_mul_f32_e32 v4, v6, v10
	v_rcp_f32_e32 v10, v5
	s_nop 0
	v_mul_f32_e32 v5, v7, v10
	v_rcp_f32_e32 v10, v8
	s_nop 0
	v_mul_f32_e32 v8, v2, v10
	v_rcp_f32_e32 v10, v9
	s_nop 0
	v_mul_f32_e32 v9, v3, v10

; #define MFMA16(a, b, c) __builtin_amdgcn_mfma_f32_16x16x32_bf16((a), (b), (c), 0, 0, 0)
; DI bf16_t f2bf(float x) { return (bf16_t)(pack2(x, 0.f) & 0xffffu); }
; DI float bf2f(bf16_t h) { return __uint_as_float(((unsigned)h) << 16); }
; DI void wave_lds_sync() { asm volatile("s_waitcnt lgkmcnt(0)" ::: "memory"); __builtin_amdgcn_wave_barrier(); }
; template <bool FINAL>
; DI void s5_item(const Params& p, int layer, int item, char* lds) {
;     ...
;     if (quad < 2) uf = *(const bf16x8*)(p.proj + (size_t)(tb + c16) * PW + C_AU + g * 16 + quad * 8);
;     float uo[FINAL ? 4 : 1];
;     if constexpr (FINAL) {
; #pragma unroll
;       for (int r = 0; r < 4; ++r) uo[r] = bf2f(p.proj[(size_t)(tb + quad * 4 + r) * PW + C_AU + g * 16 + c16]);
;     }
; #pragma unroll
;     for (int nt = 0; nt < 8; ++nt) {
;       f32x4 acc = MFMA16(uf, bbf[nt], (f32x4{0.f, 0.f, 0.f, 0.f}));
; #pragma unroll
;       for (int r = 0; r < 4; ++r) bu[(quad * 4 + r) * 128 + nt * 16 + c16] = acc[r];
;     }
;     wave_lds_sync();
; #pragma unroll
;     for (int tt = 0; tt < 16; ++tt) {
;       const float br_ = bu[tt * 128 + lane], bi_ = bu[tt * 128 + 64 + lane];
;       const float nr = are * xr - aim * xi + br_;
;       const float ni = are * xi + aim * xr + bi_;
;       xr = nr; xi = ni;
;       if constexpr (FINAL) {
;         *(bf16_t*)(xsb + tt * 256 + ((((lane >> 3)) ^ tt) << 4) + (lane & 7) * 2) = f2bf(xr);
;         *(bf16_t*)(xsb + tt * 256 + (((8 + (lane >> 3)) ^ tt) << 4) + (lane & 7) * 2) = f2bf(xi);
;       }
.LBB0_1300:
	s_or_b64 exec, exec, s[6:7]
	v_add_u32_e32 v0, s5, v75
	v_mov_b32_e32 v63, v1
	v_lshl_add_u64 v[68:69], v[0:1], 1, v[60:61]
	v_add_u32_e32 v62, 0x1200, v0
	v_lshl_add_u64 v[66:67], v[62:63], 1, v[60:61]
	v_add_u32_e32 v62, 0x2400, v0
	v_lshl_add_u64 v[64:65], v[62:63], 1, v[60:61]
	v_add_u32_e32 v0, 0x3600, v0
	v_lshl_add_u64 v[62:63], v[0:1], 1, v[60:61]
	global_load_ushort v236, v[68:69], off
	global_load_ushort v237, v[66:67], off
	global_load_ushort v238, v[64:65], off
	global_load_ushort v239, v[62:63], off
	s_waitcnt vmcnt(4)
	v_mfma_f32_16x16x32_bf16 v[92:95], v[50:53], v[2:5], 0
	v_add_u32_e32 v100, 0x400, v73
	s_add_i32 s5, s5, 0x12000
	s_cmp_eq_u32 s5, 0x48000
	v_mfma_f32_16x16x32_bf16 v[96:99], v[50:53], v[6:9], 0
	s_nop 7
	ds_write2_b32 v73, v92, v96 offset1:16
	ds_write2_b32 v73, v93, v97 offset0:128 offset1:144
	ds_write2_b32 v100, v94, v98 offset1:16
	ds_write2_b32 v100, v95, v99 offset0:128 offset1:144
	v_mfma_f32_16x16x32_bf16 v[92:95], v[50:53], v[10:13], 0
	s_waitcnt vmcnt(0)
	v_lshlrev_b32_e32 v91, 16, v236
	v_lshlrev_b32_e32 v90, 16, v237
	v_lshlrev_b32_e32 v89, 16, v238
	v_lshlrev_b32_e32 v0, 16, v239
	v_mfma_f32_16x16x32_bf16 v[96:99], v[50:53], v[14:17], 0
	s_nop 7
	ds_write2_b32 v73, v92, v96 offset0:32 offset1:48
	ds_write2_b32 v73, v93, v97 offset0:160 offset1:176
	ds_write2_b32 v100, v94, v98 offset0:32 offset1:48
	ds_write2_b32 v100, v95, v99 offset0:160 offset1:176
	v_mfma_f32_16x16x32_bf16 v[92:95], v[50:53], v[18:21], 0
	v_mfma_f32_16x16x32_bf16 v[96:99], v[50:53], v[22:25], 0
	s_nop 7
	ds_write2_b32 v73, v92, v96 offset0:64 offset1:80
	ds_write2_b32 v73, v93, v97 offset0:192 offset1:208
	ds_write2_b32 v100, v94, v98 offset0:64 offset1:80
	ds_write2_b32 v100, v95, v99 offset0:192 offset1:208
	v_mfma_f32_16x16x32_bf16 v[92:95], v[50:53], v[26:29], 0
	v_mfma_f32_16x16x32_bf16 v[50:53], v[50:53], v[30:33], 0
	s_nop 7
	ds_write2_b32 v73, v92, v50 offset0:96 offset1:112
	ds_write2_b32 v73, v93, v51 offset0:224 offset1:240
	ds_write2_b32 v100, v94, v52 offset0:96 offset1:112
	ds_write2_b32 v100, v95, v53 offset0:224 offset1:240
	s_waitcnt lgkmcnt(0)
	ds_read2st64_b32 v[232:233], v74 offset1:1
	ds_read2st64_b32 v[234:235], v74 offset0:2 offset1:3
	ds_read2st64_b32 v[236:237], v74 offset0:4 offset1:5
	ds_read2st64_b32 v[238:239], v74 offset0:6 offset1:7
	ds_read2st64_b32 v[240:241], v74 offset0:8 offset1:9
	ds_read2st64_b32 v[242:243], v74 offset0:10 offset1:11
	ds_read2st64_b32 v[244:245], v74 offset0:12 offset1:13
	ds_read2st64_b32 v[246:247], v74 offset0:14 offset1:15
	ds_read2st64_b32 v[248:249], v74 offset0:16 offset1:17
	ds_read2st64_b32 v[250:251], v74 offset0:18 offset1:19
	ds_read2st64_b32 v[252:253], v74 offset0:20 offset1:21
	ds_read2st64_b32 v[254:255], v74 offset0:22 offset1:23
	s_waitcnt lgkmcnt(11)
	v_fma_f32 v52, -v56, v71, v232
	v_fma_f32 v53, v56, v70, v233
	v_fmac_f32_e32 v52, v54, v70
	v_fmac_f32_e32 v53, v54, v71
	v_cvt_pk_bf16_f32 v50, v52, v53
	ds_write_b16 v77, v50 offset:8192
	ds_write_b16_d16_hi v77, v50 offset:8320
	s_waitcnt lgkmcnt(12)
	v_fma_f32 v70, -v56, v53, v234
	v_fma_f32 v71, v56, v52, v235
	v_fmac_f32_e32 v70, v54, v52
	v_fmac_f32_e32 v71, v54, v53
	v_cvt_pk_bf16_f32 v50, v70, v71
	ds_write_b16 v78, v50 offset:8448
	ds_write_b16_d16_hi v78, v50 offset:8576
	s_waitcnt lgkmcnt(13)
	v_fma_f32 v52, -v56, v71, v236
	v_fma_f32 v53, v56, v70, v237
	v_fmac_f32_e32 v52, v54, v70
	v_fmac_f32_e32 v53, v54, v71
	v_cvt_pk_bf16_f32 v50, v52, v53
	ds_write_b16 v79, v50 offset:8704
	ds_write_b16_d16_hi v79, v50 offset:8832
	s_waitcnt lgkmcnt(14)
	v_fma_f32 v70, -v56, v53, v238
	v_fma_f32 v71, v56, v52, v239
	v_fmac_f32_e32 v70, v54, v52
	v_fmac_f32_e32 v71, v54, v53
	v_cvt_pk_bf16_f32 v50, v70, v71
	ds_write_b16 v80, v50 offset:8960
	ds_write_b16_d16_hi v80, v50 offset:9088
	ds_read2st64_b32 v[232:233], v74 offset0:24 offset1:25
	ds_read2st64_b32 v[234:235], v74 offset0:26 offset1:27
	ds_read2st64_b32 v[236:237], v74 offset0:28 offset1:29
	ds_read2st64_b32 v[238:239], v74 offset0:30 offset1:31
	s_waitcnt lgkmcnt(15)
	v_fma_f32 v52, -v56, v71, v240
	v_fma_f32 v53, v56, v70, v241
	v_fmac_f32_e32 v52, v54, v70
	v_fmac_f32_e32 v53, v54, v71
	v_cvt_pk_bf16_f32 v50, v52, v53
	ds_write_b16 v81, v50 offset:9216
	ds_write_b16_d16_hi v81, v50 offset:9344
	s_waitcnt lgkmcnt(15)
	v_fma_f32 v70, -v56, v53, v242
	v_fma_f32 v71, v56, v52, v243
	v_fmac_f32_e32 v70, v54, v52
	v_fmac_f32_e32 v71, v54, v53
	v_cvt_pk_bf16_f32 v50, v70, v71
	ds_write_b16 v82, v50 offset:9472
	ds_write_b16_d16_hi v82, v50 offset:9600
	s_waitcnt lgkmcnt(15)
; #define MFMA16(a, b, c) __builtin_amdgcn_mfma_f32_16x16x32_bf16((a), (b), (c), 0, 0, 0)
; DI bf16_t f2bf(float x) { return (bf16_t)(pack2(x, 0.f) & 0xffffu); }
; DI void wave_lds_sync() { asm volatile("s_waitcnt lgkmcnt(0)" ::: "memory"); __builtin_amdgcn_wave_barrier(); }
; DI float gelu_tanh(float x) {
;   const float u = 0.7978845608028654f * (x + 0.044715f * x * x * x);
;   const float t = 1.f - 2.f / (1.f + __expf(2.f * u));
;   return 0.5f * x * (1.f + t);
; }
; template <bool FINAL>
; DI void s5_item(const Params& p, int layer, int item, char* lds) {
;     ...
;     for (int tt = 0; tt < 16; ++tt) {
;       const float br_ = bu[tt * 128 + lane], bi_ = bu[tt * 128 + 64 + lane];
;       const float nr = are * xr - aim * xi + br_;
;       const float ni = are * xi + aim * xr + bi_;
;       xr = nr; xi = ni;
;       if constexpr (FINAL) {
;         *(bf16_t*)(xsb + tt * 256 + ((((lane >> 3)) ^ tt) << 4) + (lane & 7) * 2) = f2bf(xr);
;         *(bf16_t*)(xsb + tt * 256 + (((8 + (lane >> 3)) ^ tt) << 4) + (lane & 7) * 2) = f2bf(xi);
;       }
;     }
;     if constexpr (FINAL) {
;       wave_lds_sync();
;       f32x4 y = f32x4{0.f, 0.f, 0.f, 0.f};
; #pragma unroll
;       for (int ks = 0; ks < 4; ++ks) {
;         const bf16x8 xf = *(const bf16x8*)(xsb + c16 * 256 + (((ks * 4 + quad) ^ c16) << 4));
;         y = MFMA16(xf, cf[ks], y);
;       }
; #pragma unroll
;       for (int r = 0; r < 4; ++r) {
;         const float v = y[r] + dsk * uo[r];
;         p.proj[(size_t)(tb + quad * 4 + r) * PW + C_AU + g * 16 + c16] = f2bf(gelu_tanh(v));
;       }
	v_fma_f32 v52, -v56, v71, v244
	v_fma_f32 v53, v56, v70, v245
	v_fmac_f32_e32 v52, v54, v70
	v_fmac_f32_e32 v53, v54, v71
	v_cvt_pk_bf16_f32 v50, v52, v53
	ds_write_b16 v83, v50 offset:9728
	ds_write_b16_d16_hi v83, v50 offset:9856
	s_waitcnt lgkmcnt(15)
	v_fma_f32 v70, -v56, v53, v246
	v_fma_f32 v71, v56, v52, v247
	v_fmac_f32_e32 v70, v54, v52
	v_fmac_f32_e32 v71, v54, v53
	v_cvt_pk_bf16_f32 v50, v70, v71
	ds_write_b16 v84, v50 offset:9984
	ds_write_b16_d16_hi v84, v50 offset:10112
	s_waitcnt lgkmcnt(15)
	v_fma_f32 v52, -v56, v71, v248
	v_fma_f32 v53, v56, v70, v249
	v_fmac_f32_e32 v52, v54, v70
	v_fmac_f32_e32 v53, v54, v71
	v_cvt_pk_bf16_f32 v50, v52, v53
	ds_write_b16 v77, v50 offset:10368
	ds_write_b16_d16_hi v77, v50 offset:10240
	s_waitcnt lgkmcnt(15)
	v_fma_f32 v70, -v56, v53, v250
	v_fma_f32 v71, v56, v52, v251
	v_fmac_f32_e32 v70, v54, v52
	v_fmac_f32_e32 v71, v54, v53
	v_cvt_pk_bf16_f32 v50, v70, v71
	ds_write_b16 v78, v50 offset:10624
	ds_write_b16_d16_hi v78, v50 offset:10496
	s_waitcnt lgkmcnt(15)
	v_fma_f32 v52, -v56, v71, v252
	v_fma_f32 v53, v56, v70, v253
	v_fmac_f32_e32 v52, v54, v70
	v_fmac_f32_e32 v53, v54, v71
	v_cvt_pk_bf16_f32 v50, v52, v53
	ds_write_b16 v79, v50 offset:10880
	ds_write_b16_d16_hi v79, v50 offset:10752
	s_waitcnt lgkmcnt(15)
	v_fma_f32 v70, -v56, v53, v254
	v_fma_f32 v71, v56, v52, v255
	v_fmac_f32_e32 v70, v54, v52
	v_fmac_f32_e32 v71, v54, v53
	v_cvt_pk_bf16_f32 v50, v70, v71
	ds_write_b16 v80, v50 offset:11136
	ds_write_b16_d16_hi v80, v50 offset:11008
	s_waitcnt lgkmcnt(15)
	v_fma_f32 v52, -v56, v71, v232
	v_fma_f32 v53, v56, v70, v233
	v_fmac_f32_e32 v52, v54, v70
	v_fmac_f32_e32 v53, v54, v71
	v_cvt_pk_bf16_f32 v50, v52, v53
	ds_write_b16 v81, v50 offset:11392
	ds_write_b16_d16_hi v81, v50 offset:11264
	s_waitcnt lgkmcnt(15)
	v_fma_f32 v70, -v56, v53, v234
	v_fma_f32 v71, v56, v52, v235
	v_fmac_f32_e32 v70, v54, v52
	v_fmac_f32_e32 v71, v54, v53
	v_cvt_pk_bf16_f32 v50, v70, v71
	ds_write_b16 v82, v50 offset:11648
	ds_write_b16_d16_hi v82, v50 offset:11520
	s_waitcnt lgkmcnt(15)
	v_fma_f32 v52, -v56, v71, v236
	v_fma_f32 v53, v56, v70, v237
	v_fmac_f32_e32 v52, v54, v70
	v_fmac_f32_e32 v53, v54, v71
	v_cvt_pk_bf16_f32 v50, v52, v53
	ds_write_b16 v83, v50 offset:11904
	ds_write_b16_d16_hi v83, v50 offset:11776
	s_waitcnt lgkmcnt(15)
	v_fma_f32 v70, -v56, v53, v238
	v_fma_f32 v71, v56, v52, v239
	v_fmac_f32_e32 v70, v54, v52
	v_fmac_f32_e32 v71, v54, v53
	v_cvt_pk_bf16_f32 v50, v70, v71
	ds_write_b16 v84, v50 offset:12160
	ds_write_b16_d16_hi v84, v50 offset:12032
	s_waitcnt lgkmcnt(0)
	ds_read_b128 v[50:53], v85 offset:8192
	ds_read_b128 v[92:95], v86 offset:8192
	ds_read_b128 v[232:235], v87 offset:8192
	ds_read_b128 v[236:239], v88 offset:8192
	s_waitcnt lgkmcnt(3)
	v_mfma_f32_16x16x32_bf16 v[50:53], v[50:53], v[34:37], 0
	s_waitcnt lgkmcnt(2)
	v_mfma_f32_16x16x32_bf16 v[50:53], v[92:95], v[38:41], v[50:53]
	s_waitcnt lgkmcnt(1)
	v_mfma_f32_16x16x32_bf16 v[50:53], v[232:235], v[42:45], v[50:53]
	s_waitcnt lgkmcnt(0)
	v_mfma_f32_16x16x32_bf16 v[50:53], v[236:239], v[46:49], v[50:53]
	s_nop 7
	v_fma_f32 v50, v72, v91, v50
	v_fma_f32 v51, v72, v90, v51
	v_fma_f32 v52, v72, v89, v52
	v_fma_f32 v53, v72, v0, v53
	v_mul_f32_e32 v92, v50, v50
	v_mul_f32_e32 v93, v51, v51
	v_mul_f32_e32 v94, v52, v52
	v_mul_f32_e32 v95, v53, v53
	v_mul_f32_e32 v92, 0x3d372713, v92
	v_mul_f32_e32 v93, 0x3d372713, v93
	v_mul_f32_e32 v94, 0x3d372713, v94
	v_mul_f32_e32 v95, 0x3d372713, v95
	v_fma_f32 v92, v92, v50, v50
	v_fma_f32 v93, v93, v51, v51
	v_fma_f32 v94, v94, v52, v52
	v_fma_f32 v95, v95, v53, v53
	v_mul_f32_e32 v92, 0xc0135761, v92
	v_mul_f32_e32 v93, 0xc0135761, v93
	v_mul_f32_e32 v94, 0xc0135761, v94
	v_mul_f32_e32 v95, 0xc0135761, v95
	v_exp_f32_e32 v92, v92
	v_exp_f32_e32 v93, v93
	v_exp_f32_e32 v94, v94
	v_exp_f32_e32 v95, v95
	v_add_f32_e32 v92, 1.0, v92
	v_add_f32_e32 v93, 1.0, v93
	v_add_f32_e32 v94, 1.0, v94
	v_add_f32_e32 v95, 1.0, v95
	v_rcp_f32_e32 v92, v92
	v_rcp_f32_e32 v93, v93
	v_rcp_f32_e32 v94, v94
	v_rcp_f32_e32 v95, v95
	v_mul_f32_e32 v50, v50, v92
	v_mul_f32_e32 v51, v51, v93
	v_mul_f32_e32 v52, v52, v94
	v_mul_f32_e32 v53, v53, v95
	v_cvt_pk_bf16_f32 v50, v50, s0
	v_cvt_pk_bf16_f32 v51, v51, s0
	v_cvt_pk_bf16_f32 v52, v52, s0
	v_cvt_pk_bf16_f32 v53, v53, s0
	global_store_short v[68:69], v50, off
	global_store_short v[66:67], v51, off
	global_store_short v[64:65], v52, off
	global_store_short v[62:63], v53, off
	s_waitcnt lgkmcnt(0)
	s_cbranch_scc1 .LBB0_1303

; #define MFMA16(a, b, c) __builtin_amdgcn_mfma_f32_16x16x32_bf16((a), (b), (c), 0, 0, 0)
; template <int EPI>
; DI void gemm_tile(const GemmArgs& ga, const EpiArgs& ea, int m0, int n0, char* lds) {
;     ...
;   for (int kt = 0; kt < nk; ++kt) {
;     if (kt + 1 < nk) asm volatile("s_waitcnt vmcnt(6)" ::: "memory");
;     else asm volatile("s_waitcnt vmcnt(0)" ::: "memory");
;     __builtin_amdgcn_s_barrier();
;     const char* Ab = lds + (kt % 3) * 24576 + wm * 128 * 64;
;     const char* Bb = lds + (kt % 3) * 24576 + 16384 + wn * 64 * 64;
;     bf16x8 af[8], bfr[4];
;     const int ch = swz64(c16, quad) << 4;
; #pragma unroll
;     for (int nt = 0; nt < 4; ++nt) bfr[nt] = *(const bf16x8*)(Bb + (nt * 16 + c16) * 64 + ch);
; #pragma unroll
;     for (int mt = 0; mt < 2; ++mt) af[mt] = *(const bf16x8*)(Ab + (mt * 16 + c16) * 64 + ch);
;     __builtin_amdgcn_sched_barrier(0);
;     if (kt + 2 < nk) dma(kt + 2, (kt + 2) % 3);
;     __builtin_amdgcn_sched_barrier(0);
; #pragma unroll
;     for (int g = 0; g < 4; ++g) {
;       if (g < 3) {
; #pragma unroll
;         for (int mt = 2 * g + 2; mt < 2 * g + 4; ++mt) af[mt] = *(const bf16x8*)(Ab + (mt * 16 + c16) * 64 + ch);
;       }
; #pragma unroll
;       for (int mt = 2 * g; mt < 2 * g + 2; ++mt)
; #pragma unroll
;         for (int nt = 0; nt < 4; ++nt) acc[mt][nt] = MFMA16(bfr[nt], af[mt], acc[mt][nt]);
;       __builtin_amdgcn_sched_barrier(0);
;     }
.LBB0_1458:
	s_mul_hi_u32 s25, s23, 0xaaaaaaab
	s_lshr_b32 s25, s25, 1
	s_mul_i32 s25, s25, 0xfffee000
	v_or_b32_e32 v168, s25, v165
	v_add_u32_e32 v196, v167, v168
	s_waitcnt vmcnt(6)
	s_barrier
	v_add_u32_e32 v212, v166, v168
	ds_read_b128 v[168:171], v196 offset:16384
	ds_read_b128 v[188:191], v196 offset:17408
	ds_read_b128 v[192:195], v196 offset:18432
	ds_read_b128 v[196:199], v196 offset:19456
	ds_read_b128 v[200:203], v212
	ds_read_b128 v[204:207], v212 offset:1024
	s_add_i32 s23, s23, 1
	s_mul_i32 s25, s24, 0xab
	s_bfe_u32 s25, s25, 0x70009
	s_mul_i32 s25, s25, 3
	s_sub_i32 s25, s24, s25
	s_and_b32 s25, s25, 0xff
	s_mulk_i32 s25, 0x6000
	s_add_i32 s25, s25, 16
	v_add_u32_e32 v210, s25, v159
	v_lshl_add_u64 v[208:209], v[130:131], 0, s[0:1]
	v_readfirstlane_b32 s26, v210
	v_add_u32_e32 v210, s25, v157
	s_mov_b32 m0, s26
	v_readfirstlane_b32 s26, v210
	v_add_u32_e32 v210, s25, v147
	global_load_lds_dwordx4 v[208:209], off
	v_lshl_add_u64 v[208:209], v[132:133], 0, s[0:1]
	s_mov_b32 m0, s26
	v_readfirstlane_b32 s26, v210
	v_add_u32_e32 v210, s25, v146
	global_load_lds_dwordx4 v[208:209], off
	v_lshl_add_u64 v[208:209], v[134:135], 0, s[0:1]
	s_mov_b32 m0, s26
	v_readfirstlane_b32 s26, v210
	v_add_u32_e32 v210, s25, v145
	global_load_lds_dwordx4 v[208:209], off
	v_lshl_add_u64 v[208:209], v[136:137], 0, s[0:1]
	s_mov_b32 m0, s26
	v_readfirstlane_b32 s26, v210
	v_add_u32_e32 v210, s25, v160
	global_load_lds_dwordx4 v[208:209], off
	v_lshl_add_u64 v[208:209], v[138:139], 0, s[0:1]
	s_mov_b32 m0, s26
	v_readfirstlane_b32 s25, v210
	global_load_lds_dwordx4 v[208:209], off
	v_lshl_add_u64 v[208:209], v[140:141], 0, s[0:1]
	s_mov_b32 m0, s25
	s_nop 0
	global_load_lds_dwordx4 v[208:209], off
	s_waitcnt lgkmcnt(0)
	v_mfma_f32_16x16x32_bf16 v[126:129], v[168:171], v[200:203], v[126:129]
	v_mfma_f32_16x16x32_bf16 v[122:125], v[188:191], v[200:203], v[122:125]
	v_mfma_f32_16x16x32_bf16 v[118:121], v[192:195], v[200:203], v[118:121]
	v_mfma_f32_16x16x32_bf16 v[114:117], v[196:199], v[200:203], v[114:117]
	ds_read_b128 v[200:203], v212 offset:2048
	ds_read_b128 v[208:211], v212 offset:3072
	v_mfma_f32_16x16x32_bf16 v[106:109], v[168:171], v[204:207], v[106:109]
	v_mfma_f32_16x16x32_bf16 v[98:101], v[188:191], v[204:207], v[98:101]
	v_mfma_f32_16x16x32_bf16 v[86:89], v[192:195], v[204:207], v[86:89]
	v_mfma_f32_16x16x32_bf16 v[74:77], v[196:199], v[204:207], v[74:77]
	s_waitcnt lgkmcnt(0)
	v_mfma_f32_16x16x32_bf16 v[70:73], v[168:171], v[200:203], v[70:73]
	v_mfma_f32_16x16x32_bf16 v[66:69], v[188:191], v[200:203], v[66:69]
	v_mfma_f32_16x16x32_bf16 v[62:65], v[192:195], v[200:203], v[62:65]
	v_mfma_f32_16x16x32_bf16 v[58:61], v[196:199], v[200:203], v[58:61]
	ds_read_b128 v[200:203], v212 offset:4096
	ds_read_b128 v[204:207], v212 offset:5120
	v_mfma_f32_16x16x32_bf16 v[54:57], v[168:171], v[208:211], v[54:57]
	v_mfma_f32_16x16x32_bf16 v[50:53], v[188:191], v[208:211], v[50:53]
	v_mfma_f32_16x16x32_bf16 v[46:49], v[192:195], v[208:211], v[46:49]
	v_mfma_f32_16x16x32_bf16 v[42:45], v[196:199], v[208:211], v[42:45]
	s_waitcnt lgkmcnt(0)
	v_mfma_f32_16x16x32_bf16 v[38:41], v[168:171], v[200:203], v[38:41]
	v_mfma_f32_16x16x32_bf16 v[34:37], v[188:191], v[200:203], v[34:37]
	v_mfma_f32_16x16x32_bf16 v[30:33], v[192:195], v[200:203], v[30:33]
	v_mfma_f32_16x16x32_bf16 v[26:29], v[196:199], v[200:203], v[26:29]
	ds_read_b128 v[200:203], v212 offset:6144
	ds_read_b128 v[208:211], v212 offset:7168
	v_mfma_f32_16x16x32_bf16 v[22:25], v[168:171], v[204:207], v[22:25]
	v_mfma_f32_16x16x32_bf16 v[18:21], v[188:191], v[204:207], v[18:21]
	v_mfma_f32_16x16x32_bf16 v[14:17], v[192:195], v[204:207], v[14:17]
	v_mfma_f32_16x16x32_bf16 v[10:13], v[196:199], v[204:207], v[10:13]
	s_waitcnt lgkmcnt(0)
	v_mfma_f32_16x16x32_bf16 v[6:9], v[168:171], v[200:203], v[6:9]
	v_mfma_f32_16x16x32_bf16 v[2:5], v[188:191], v[200:203], v[2:5]
	v_mfma_f32_16x16x32_bf16 v[78:81], v[192:195], v[200:203], v[78:81]
	v_mfma_f32_16x16x32_bf16 v[82:85], v[196:199], v[200:203], v[82:85]
	v_mfma_f32_16x16x32_bf16 v[90:93], v[168:171], v[208:211], v[90:93]
	v_mfma_f32_16x16x32_bf16 v[94:97], v[188:191], v[208:211], v[94:97]
	v_mfma_f32_16x16x32_bf16 v[102:105], v[192:195], v[208:211], v[102:105]
	v_mfma_f32_16x16x32_bf16 v[110:113], v[196:199], v[208:211], v[110:113]
	s_add_i32 s24, s24, 1
	s_add_u32 s0, s0, 64
	s_addc_u32 s1, s1, 0
	v_add_u32_e32 v167, 0x6000, v167
	s_cmpk_lg_i32 s0, 0x380
	v_add_u32_e32 v166, 0x6000, v166
	s_cbranch_scc1 .LBB0_1458
	s_add_i32 s0, 16, 0xc000
	v_add_u32_e32 v130, s0, v164
	v_add3_u32 v145, v130, v156, v158
	s_waitcnt vmcnt(6)
	s_barrier
; #define MFMA16(a, b, c) __builtin_amdgcn_mfma_f32_16x16x32_bf16((a), (b), (c), 0, 0, 0)
; template <int EPI>
; DI void gemm_tile(const GemmArgs& ga, const EpiArgs& ea, int m0, int n0, char* lds) {
;     ...
;   for (int kt = 0; kt < nk; ++kt) {
;     if (kt + 1 < nk) asm volatile("s_waitcnt vmcnt(6)" ::: "memory");
;     else asm volatile("s_waitcnt vmcnt(0)" ::: "memory");
;     __builtin_amdgcn_s_barrier();
;     const char* Ab = lds + (kt % 3) * 24576 + wm * 128 * 64;
;     const char* Bb = lds + (kt % 3) * 24576 + 16384 + wn * 64 * 64;
;     bf16x8 af[8], bfr[4];
;     const int ch = swz64(c16, quad) << 4;
; #pragma unroll
;     for (int nt = 0; nt < 4; ++nt) bfr[nt] = *(const bf16x8*)(Bb + (nt * 16 + c16) * 64 + ch);
; #pragma unroll
;     for (int mt = 0; mt < 2; ++mt) af[mt] = *(const bf16x8*)(Ab + (mt * 16 + c16) * 64 + ch);
;     __builtin_amdgcn_sched_barrier(0);
;     if (kt + 2 < nk) dma(kt + 2, (kt + 2) % 3);
;     __builtin_amdgcn_sched_barrier(0);
; #pragma unroll
;     for (int g = 0; g < 4; ++g) {
;       if (g < 3) {
; #pragma unroll
;         for (int mt = 2 * g + 2; mt < 2 * g + 4; ++mt) af[mt] = *(const bf16x8*)(Ab + (mt * 16 + c16) * 64 + ch);
;       }
; #pragma unroll
;       for (int mt = 2 * g; mt < 2 * g + 2; ++mt)
; #pragma unroll
;         for (int nt = 0; nt < 4; ++nt) acc[mt][nt] = MFMA16(bfr[nt], af[mt], acc[mt][nt]);
;       __builtin_amdgcn_sched_barrier(0);
;     }
	ds_read_b128 v[130:133], v145 offset:16384
	ds_read_b128 v[134:137], v145 offset:17408
	ds_read_b128 v[138:141], v145 offset:18432
	ds_read_b128 v[164:167], v145 offset:19456
	v_add_u32_e32 v145, s0, v163
	v_add3_u32 v145, v145, v156, v158
	ds_read_b128 v[168:171], v145
	ds_read_b128 v[188:191], v145 offset:1024
	s_waitcnt lgkmcnt(0)
	v_mfma_f32_16x16x32_bf16 v[126:129], v[130:133], v[168:171], v[126:129]
	v_mfma_f32_16x16x32_bf16 v[192:195], v[134:137], v[168:171], v[122:125]
	v_mfma_f32_16x16x32_bf16 v[118:121], v[138:141], v[168:171], v[118:121]
	v_mfma_f32_16x16x32_bf16 v[168:171], v[164:167], v[168:171], v[114:117]
	s_nop 2
	ds_read_b128 v[114:117], v145 offset:2048
	ds_read_b128 v[122:125], v145 offset:3072
	v_mfma_f32_16x16x32_bf16 v[106:109], v[130:133], v[188:191], v[106:109]
	v_mfma_f32_16x16x32_bf16 v[98:101], v[134:137], v[188:191], v[98:101]
	v_mfma_f32_16x16x32_bf16 v[86:89], v[138:141], v[188:191], v[86:89]
	v_mfma_f32_16x16x32_bf16 v[74:77], v[164:167], v[188:191], v[74:77]
	s_waitcnt lgkmcnt(0)
	v_mfma_f32_16x16x32_bf16 v[70:73], v[130:133], v[114:117], v[70:73]
	v_mfma_f32_16x16x32_bf16 v[66:69], v[134:137], v[114:117], v[66:69]
	v_mfma_f32_16x16x32_bf16 v[62:65], v[138:141], v[114:117], v[62:65]
	v_mfma_f32_16x16x32_bf16 v[58:61], v[164:167], v[114:117], v[58:61]
	ds_read_b128 v[114:117], v145 offset:4096
	ds_read_b128 v[188:191], v145 offset:5120
	v_mfma_f32_16x16x32_bf16 v[54:57], v[130:133], v[122:125], v[54:57]
	v_mfma_f32_16x16x32_bf16 v[50:53], v[134:137], v[122:125], v[50:53]
	v_mfma_f32_16x16x32_bf16 v[46:49], v[138:141], v[122:125], v[46:49]
	v_mfma_f32_16x16x32_bf16 v[42:45], v[164:167], v[122:125], v[42:45]
	s_waitcnt lgkmcnt(0)
	v_mfma_f32_16x16x32_bf16 v[38:41], v[130:133], v[114:117], v[38:41]
	v_mfma_f32_16x16x32_bf16 v[34:37], v[134:137], v[114:117], v[34:37]
	v_mfma_f32_16x16x32_bf16 v[30:33], v[138:141], v[114:117], v[30:33]
	v_mfma_f32_16x16x32_bf16 v[26:29], v[164:167], v[114:117], v[26:29]
	ds_read_b128 v[114:117], v145 offset:6144
	ds_read_b128 v[122:125], v145 offset:7168
	v_mfma_f32_16x16x32_bf16 v[22:25], v[130:133], v[188:191], v[22:25]
	v_mfma_f32_16x16x32_bf16 v[18:21], v[134:137], v[188:191], v[18:21]
	v_mfma_f32_16x16x32_bf16 v[14:17], v[138:141], v[188:191], v[14:17]
	v_mfma_f32_16x16x32_bf16 v[10:13], v[164:167], v[188:191], v[10:13]
	s_waitcnt lgkmcnt(0)
	v_mfma_f32_16x16x32_bf16 v[6:9], v[130:133], v[114:117], v[6:9]
	v_mfma_f32_16x16x32_bf16 v[2:5], v[134:137], v[114:117], v[2:5]
	v_mfma_f32_16x16x32_bf16 v[188:191], v[138:141], v[114:117], v[78:81]
	v_mfma_f32_16x16x32_bf16 v[196:199], v[164:167], v[114:117], v[82:85]
	v_mfma_f32_16x16x32_bf16 v[130:133], v[130:133], v[122:125], v[90:93]
	v_mfma_f32_16x16x32_bf16 v[134:137], v[134:137], v[122:125], v[94:97]
	v_mfma_f32_16x16x32_bf16 v[138:141], v[138:141], v[122:125], v[102:105]
	v_mfma_f32_16x16x32_bf16 v[164:167], v[164:167], v[122:125], v[110:113]
	v_add3_u32 v78, v162, v156, v158
	s_waitcnt vmcnt(0)
	s_barrier
	ds_read_b128 v[200:203], v78 offset:16384
	ds_read_b128 v[204:207], v78 offset:17408
	ds_read_b128 v[208:211], v78 offset:18432
	ds_read_b128 v[212:215], v78 offset:19456
	v_add3_u32 v145, v161, v156, v158
	ds_read_b128 v[78:81], v145
	ds_read_b128 v[82:85], v145 offset:1024
	s_waitcnt lgkmcnt(0)
	v_mfma_f32_16x16x32_bf16 v[122:125], v[200:203], v[78:81], v[126:129]
	v_mfma_f32_16x16x32_bf16 v[114:117], v[204:207], v[78:81], v[192:195]
	v_mfma_f32_16x16x32_bf16 v[156:159], v[208:211], v[78:81], v[118:121]
	v_mfma_f32_16x16x32_bf16 v[118:121], v[212:215], v[78:81], v[168:171]
	ds_read_b128 v[78:81], v145 offset:2048
	ds_read_b128 v[126:129], v145 offset:3072
	v_mfma_f32_16x16x32_bf16 v[106:109], v[200:203], v[82:85], v[106:109]
	v_mfma_f32_16x16x32_bf16 v[98:101], v[204:207], v[82:85], v[98:101]
	v_mfma_f32_16x16x32_bf16 v[110:113], v[208:211], v[82:85], v[86:89]
	v_mfma_f32_16x16x32_bf16 v[102:105], v[212:215], v[82:85], v[74:77]
	s_waitcnt lgkmcnt(0)
	v_mfma_f32_16x16x32_bf16 v[90:93], v[200:203], v[78:81], v[70:73]
	v_mfma_f32_16x16x32_bf16 v[82:85], v[204:207], v[78:81], v[66:69]
	v_mfma_f32_16x16x32_bf16 v[94:97], v[208:211], v[78:81], v[62:65]
	v_mfma_f32_16x16x32_bf16 v[86:89], v[212:215], v[78:81], v[58:61]
	v_mfma_f32_16x16x32_bf16 v[78:81], v[208:211], v[126:129], v[46:49]
	s_nop 2
	ds_read_b128 v[46:49], v145 offset:4096
	ds_read_b128 v[160:163], v145 offset:5120
	v_mfma_f32_16x16x32_bf16 v[74:77], v[200:203], v[126:129], v[54:57]
	v_mfma_f32_16x16x32_bf16 v[66:69], v[204:207], v[126:129], v[50:53]
	v_mfma_f32_16x16x32_bf16 v[70:73], v[212:215], v[126:129], v[42:45]
	s_waitcnt lgkmcnt(0)
	v_mfma_f32_16x16x32_bf16 v[58:61], v[200:203], v[46:49], v[38:41]
	v_mfma_f32_16x16x32_bf16 v[50:53], v[204:207], v[46:49], v[34:37]
	v_mfma_f32_16x16x32_bf16 v[62:65], v[208:211], v[46:49], v[30:33]
	v_mfma_f32_16x16x32_bf16 v[54:57], v[212:215], v[46:49], v[26:29]
	v_mfma_f32_16x16x32_bf16 v[46:49], v[208:211], v[160:163], v[14:17]
	s_nop 2
	ds_read_b128 v[14:17], v145 offset:6144
	ds_read_b128 v[126:129], v145 offset:7168
	v_mfma_f32_16x16x32_bf16 v[42:45], v[200:203], v[160:163], v[22:25]
	v_mfma_f32_16x16x32_bf16 v[34:37], v[204:207], v[160:163], v[18:21]
	v_mfma_f32_16x16x32_bf16 v[38:41], v[212:215], v[160:163], v[10:13]
	s_waitcnt lgkmcnt(0)
; DI unsigned pack2(float a, float b) { f2_t v = {a, b}; return __builtin_bit_cast(unsigned, __builtin_convertvector(v, bf2_t)); }
; DI float sigmoidf_(float x) { return 1.f / (1.f + __expf(-x)); }
; template <int EPI>
; DI void gemm_tile(const GemmArgs& ga, const EpiArgs& ea, int m0, int n0, char* lds) {
;     ...
;   } else if constexpr (EPI == EPI_GLU) {
;     const int blk = (n0 + wn * 64) >> 6;
; #pragma unroll
;     for (int mt = 0; mt < 8; ++mt) {
;       const int row = m0 + wm * 128 + mt * 16 + c16;
; #pragma unroll
;       for (int nt = 0; nt < 2; ++nt) {
;         const int j0 = blk * 32 + nt * 16 + quad * 4;
;         uint2* q = (uint2*)(p.proj + (size_t)row * PW + C_AG + j0);
;         const uint2 gv = *q;
;         const float g0 = __uint_as_float(gv.x << 16), g1 = __uint_as_float(gv.x & 0xffff0000u);
;         const float g2 = __uint_as_float(gv.y << 16), g3 = __uint_as_float(gv.y & 0xffff0000u);
;         uint2 o;
;         o.x = pack2(acc[mt][nt][0] * sigmoidf_(acc[mt][nt + 2][0]) * g0, acc[mt][nt][1] * sigmoidf_(acc[mt][nt + 2][1]) * g1);
;         o.y = pack2(acc[mt][nt][2] * sigmoidf_(acc[mt][nt + 2][2]) * g2, acc[mt][nt][3] * sigmoidf_(acc[mt][nt + 2][3]) * g3);
;         *q = o;
;       }
;     }
	v_mfma_f32_16x16x32_bf16 v[26:29], v[200:203], v[14:17], v[6:9]
	v_mfma_f32_16x16x32_bf16 v[18:21], v[204:207], v[14:17], v[2:5]
	v_mfma_f32_16x16x32_bf16 v[30:33], v[208:211], v[14:17], v[188:191]
	v_mfma_f32_16x16x32_bf16 v[22:25], v[212:215], v[14:17], v[196:199]
	v_mfma_f32_16x16x32_bf16 v[10:13], v[200:203], v[126:129], v[130:133]
	v_mfma_f32_16x16x32_bf16 v[2:5], v[204:207], v[126:129], v[134:137]
	v_mfma_f32_16x16x32_bf16 v[14:17], v[208:211], v[126:129], v[138:141]
	v_mfma_f32_16x16x32_bf16 v[6:9], v[212:215], v[126:129], v[164:167]
	v_lshl_or_b32 v126, v144, 6, s8
	v_and_b32_e32 v127, 0xffffff80, v142
	v_ashrrev_i32_e32 v126, 1, v126
	v_add_u32_e32 v127, s22, v127
	v_lshl_or_b32 v128, v143, 2, v126
	v_or_b32_e32 v0, v127, v0
	v_mov_b64_e32 v[126:127], s[78:79]
	v_ashrrev_i32_e32 v129, 31, v128
	v_mad_i64_i32 v[130:131], s[0:1], v0, s35, v[126:127]
	v_lshlrev_b64 v[128:129], 1, v[128:129]
	v_lshl_add_u64 v[130:131], v[130:131], 0, v[128:129]
	global_load_dwordx2 v[132:133], v[130:131], off offset:1024
	v_mul_f32_e32 v136, 0xbfb8aa3b, v156
	v_mul_f32_e32 v137, 0xbfb8aa3b, v157
	v_exp_f32_e32 v136, v136
	v_exp_f32_e32 v137, v137
	v_mul_f32_e32 v118, 0xbfb8aa3b, v118
	v_mul_f32_e32 v119, 0xbfb8aa3b, v119
	v_exp_f32_e32 v118, v118
	v_pk_add_f32 v[136:137], v[136:137], 1.0 op_sel_hi:[1,0]
	v_exp_f32_e32 v119, v119
	s_nop 0
	v_pk_add_f32 v[118:119], v[118:119], 1.0 op_sel_hi:[1,0]
	s_nop 0
	v_mul_f32_e32 v110, 0xbfb8aa3b, v110
	s_nop 0
	v_mul_f32_e32 v111, 0xbfb8aa3b, v111
	v_rcp_f32_e32 v137, v137
	s_nop 0
	s_nop 0
	v_exp_f32_e32 v110, v110
	s_nop 0
	v_exp_f32_e32 v111, v111
	s_nop 0
	v_mul_f32_e32 v102, 0xbfb8aa3b, v102
	v_rcp_f32_e32 v136, v136
	s_nop 0
	v_pk_mul_f32 v[122:123], v[122:123], v[136:137]
	v_pk_add_f32 v[110:111], v[110:111], 1.0 op_sel_hi:[1,0]
	v_mul_f32_e32 v103, 0xbfb8aa3b, v103
	v_exp_f32_e32 v102, v102
	v_exp_f32_e32 v103, v103
	v_mul_f32_e32 v94, 0xbfb8aa3b, v94
	v_mul_f32_e32 v95, 0xbfb8aa3b, v95
	v_exp_f32_e32 v94, v94
	v_pk_add_f32 v[102:103], v[102:103], 1.0 op_sel_hi:[1,0]
	v_exp_f32_e32 v95, v95
	v_mul_f32_e32 v86, 0xbfb8aa3b, v86
	v_mul_f32_e32 v87, 0xbfb8aa3b, v87
	v_exp_f32_e32 v86, v86
	v_pk_add_f32 v[94:95], v[94:95], 1.0 op_sel_hi:[1,0]
	v_exp_f32_e32 v87, v87
	v_mul_f32_e32 v78, 0xbfb8aa3b, v78
	v_mul_f32_e32 v79, 0xbfb8aa3b, v79
	v_exp_f32_e32 v78, v78
	v_pk_add_f32 v[86:87], v[86:87], 1.0 op_sel_hi:[1,0]
	v_exp_f32_e32 v79, v79
	v_mul_f32_e32 v70, 0xbfb8aa3b, v70
	v_mul_f32_e32 v71, 0xbfb8aa3b, v71
	v_exp_f32_e32 v70, v70
	v_pk_add_f32 v[78:79], v[78:79], 1.0 op_sel_hi:[1,0]
	v_exp_f32_e32 v71, v71
	v_mul_f32_e32 v62, 0xbfb8aa3b, v62
	v_mul_f32_e32 v63, 0xbfb8aa3b, v63
	v_exp_f32_e32 v62, v62
	v_pk_add_f32 v[70:71], v[70:71], 1.0 op_sel_hi:[1,0]
	v_exp_f32_e32 v63, v63
	v_mul_f32_e32 v54, 0xbfb8aa3b, v54
	v_mul_f32_e32 v55, 0xbfb8aa3b, v55
	v_exp_f32_e32 v54, v54
	v_pk_add_f32 v[62:63], v[62:63], 1.0 op_sel_hi:[1,0]
	v_exp_f32_e32 v55, v55
	v_mul_f32_e32 v46, 0xbfb8aa3b, v46
	v_mul_f32_e32 v47, 0xbfb8aa3b, v47
	v_exp_f32_e32 v46, v46
	s_waitcnt vmcnt(0)
	v_lshlrev_b32_e32 v134, 16, v132
	v_and_b32_e32 v135, 0xffff0000, v132
	v_pk_mul_f32 v[122:123], v[122:123], v[134:135]
	v_lshlrev_b32_e32 v132, 16, v133
	v_cvt_pk_bf16_f32 v122, v122, v123
	v_mul_f32_e32 v123, 0xbfb8aa3b, v158
	v_exp_f32_e32 v134, v123
	v_mul_f32_e32 v123, 0xbfb8aa3b, v159
	v_exp_f32_e32 v135, v123
	v_and_b32_e32 v133, 0xffff0000, v133
	v_pk_add_f32 v[54:55], v[54:55], 1.0 op_sel_hi:[1,0]
	v_exp_f32_e32 v47, v47
	v_pk_add_f32 v[134:135], v[134:135], 1.0 op_sel_hi:[1,0]
	v_mul_f32_e32 v38, 0xbfb8aa3b, v38
	s_nop 0
	v_pk_add_f32 v[46:47], v[46:47], 1.0 op_sel_hi:[1,0]
	s_nop 0
	v_mul_f32_e32 v39, 0xbfb8aa3b, v39
	s_nop 0
	v_exp_f32_e32 v38, v38
	v_rcp_f32_e32 v135, v135
	s_nop 0
	s_nop 0
	v_exp_f32_e32 v39, v39
	s_nop 0
	v_mul_f32_e32 v30, 0xbfb8aa3b, v30
	s_nop 0
	v_mul_f32_e32 v31, 0xbfb8aa3b, v31
	v_rcp_f32_e32 v134, v134
	s_nop 0
	v_pk_mul_f32 v[124:125], v[124:125], v[134:135]
	v_pk_add_f32 v[38:39], v[38:39], 1.0 op_sel_hi:[1,0]
	v_pk_mul_f32 v[124:125], v[124:125], v[132:133]
	s_nop 0
	v_cvt_pk_bf16_f32 v123, v124, v125
	s_nop 0
	global_store_dwordx2 v[130:131], v[122:123], off offset:1024
	s_nop 0
	global_load_dwordx2 v[122:123], v[130:131], off offset:1056
	s_nop 0
	v_exp_f32_e32 v30, v30
	s_nop 0
	v_exp_f32_e32 v31, v31
	s_nop 0
	v_mul_f32_e32 v22, 0xbfb8aa3b, v22
	v_rcp_f32_e32 v119, v119
	s_nop 0
	s_nop 0
	v_pk_add_f32 v[30:31], v[30:31], 1.0 op_sel_hi:[1,0]
	s_nop 0
	v_mul_f32_e32 v23, 0xbfb8aa3b, v23
	s_nop 0
	v_exp_f32_e32 v22, v22
	v_rcp_f32_e32 v118, v118
	s_nop 0
	v_pk_mul_f32 v[114:115], v[114:115], v[118:119]
	v_exp_f32_e32 v23, v23
	s_add_i32 s5, s5, 1
	v_pk_add_f32 v[22:23], v[22:23], 1.0 op_sel_hi:[1,0]
	s_waitcnt vmcnt(0)
	v_lshlrev_b32_e32 v124, 16, v122
	v_and_b32_e32 v125, 0xffff0000, v122
	v_pk_mul_f32 v[114:115], v[114:115], v[124:125]
	v_lshlrev_b32_e32 v122, 16, v123
	v_cvt_pk_bf16_f32 v114, v114, v115
	v_mul_f32_e32 v115, 0xbfb8aa3b, v120
	v_exp_f32_e32 v118, v115
	v_mul_f32_e32 v115, 0xbfb8aa3b, v121
	v_exp_f32_e32 v119, v115
	v_and_b32_e32 v123, 0xffff0000, v123
	v_pk_add_f32 v[118:119], v[118:119], 1.0 op_sel_hi:[1,0]
	s_nop 0
	v_rcp_f32_e32 v119, v119
	s_nop 0
	v_rcp_f32_e32 v118, v118
	s_nop 0
	v_pk_mul_f32 v[116:117], v[116:117], v[118:119]
	s_nop 0
	v_pk_mul_f32 v[116:117], v[116:117], v[122:123]
	s_nop 0
	v_cvt_pk_bf16_f32 v115, v116, v117
	s_nop 0
	global_store_dwordx2 v[130:131], v[114:115], off offset:1056
	s_nop 0
	v_or_b32_e32 v114, 16, v0
	s_nop 0
	v_mad_i64_i32 v[114:115], s[0:1], v114, s35, v[126:127]
	s_nop 0
	v_lshl_add_u64 v[114:115], v[114:115], 0, v[128:129]
	s_nop 0
	global_load_dwordx2 v[116:117], v[114:115], off offset:1024
	v_rcp_f32_e32 v111, v111
	s_nop 0
	s_nop 0
	s_waitcnt vmcnt(0)
; DI unsigned pack2(float a, float b) { f2_t v = {a, b}; return __builtin_bit_cast(unsigned, __builtin_convertvector(v, bf2_t)); }
; DI float sigmoidf_(float x) { return 1.f / (1.f + __expf(-x)); }
; template <int EPI>
; DI void gemm_tile(const GemmArgs& ga, const EpiArgs& ea, int m0, int n0, char* lds) {
;     ...
;   } else if constexpr (EPI == EPI_GLU) {
;     const int blk = (n0 + wn * 64) >> 6;
; #pragma unroll
;     for (int mt = 0; mt < 8; ++mt) {
;       const int row = m0 + wm * 128 + mt * 16 + c16;
; #pragma unroll
;       for (int nt = 0; nt < 2; ++nt) {
;         const int j0 = blk * 32 + nt * 16 + quad * 4;
;         uint2* q = (uint2*)(p.proj + (size_t)row * PW + C_AG + j0);
;         const uint2 gv = *q;
;         const float g0 = __uint_as_float(gv.x << 16), g1 = __uint_as_float(gv.x & 0xffff0000u);
;         const float g2 = __uint_as_float(gv.y << 16), g3 = __uint_as_float(gv.y & 0xffff0000u);
;         uint2 o;
;         o.x = pack2(acc[mt][nt][0] * sigmoidf_(acc[mt][nt + 2][0]) * g0, acc[mt][nt][1] * sigmoidf_(acc[mt][nt + 2][1]) * g1);
;         o.y = pack2(acc[mt][nt][2] * sigmoidf_(acc[mt][nt + 2][2]) * g2, acc[mt][nt][3] * sigmoidf_(acc[mt][nt + 2][3]) * g3);
;         *q = o;
;       }
;     }
	s_nop 0
	v_lshlrev_b32_e32 v118, 16, v116
	v_rcp_f32_e32 v110, v110
	s_nop 0
	v_and_b32_e32 v119, 0xffff0000, v116
	v_pk_mul_f32 v[106:107], v[106:107], v[110:111]
	v_lshlrev_b32_e32 v116, 16, v117
	v_pk_mul_f32 v[106:107], v[106:107], v[118:119]
	v_and_b32_e32 v117, 0xffff0000, v117
	v_cvt_pk_bf16_f32 v106, v106, v107
	v_mul_f32_e32 v107, 0xbfb8aa3b, v112
	v_exp_f32_e32 v110, v107
	v_mul_f32_e32 v107, 0xbfb8aa3b, v113
	v_exp_f32_e32 v111, v107
	s_nop 0
	v_pk_add_f32 v[110:111], v[110:111], 1.0 op_sel_hi:[1,0]
	s_nop 0
	v_rcp_f32_e32 v111, v111
	s_nop 0
	v_rcp_f32_e32 v110, v110
	s_nop 0
	v_pk_mul_f32 v[108:109], v[108:109], v[110:111]
	s_nop 0
	v_pk_mul_f32 v[108:109], v[108:109], v[116:117]
	s_nop 0
	v_cvt_pk_bf16_f32 v107, v108, v109
	s_nop 0
	global_store_dwordx2 v[114:115], v[106:107], off offset:1024
	s_nop 0
	global_load_dwordx2 v[106:107], v[114:115], off offset:1056
	v_rcp_f32_e32 v103, v103
	s_nop 0
	s_nop 0
	s_waitcnt vmcnt(0)
	s_nop 0
	v_lshlrev_b32_e32 v108, 16, v106
	v_rcp_f32_e32 v102, v102
	s_nop 0
	v_and_b32_e32 v109, 0xffff0000, v106
	v_pk_mul_f32 v[98:99], v[98:99], v[102:103]
	v_lshlrev_b32_e32 v106, 16, v107
	v_pk_mul_f32 v[98:99], v[98:99], v[108:109]
	v_and_b32_e32 v107, 0xffff0000, v107
	v_cvt_pk_bf16_f32 v98, v98, v99
	v_mul_f32_e32 v99, 0xbfb8aa3b, v104
	v_exp_f32_e32 v102, v99
	v_mul_f32_e32 v99, 0xbfb8aa3b, v105
	v_exp_f32_e32 v103, v99
	s_nop 0
	v_pk_add_f32 v[102:103], v[102:103], 1.0 op_sel_hi:[1,0]
	s_nop 0
	v_rcp_f32_e32 v103, v103
	s_nop 0
	v_rcp_f32_e32 v102, v102
	s_nop 0
	v_pk_mul_f32 v[100:101], v[100:101], v[102:103]
	s_nop 0
	v_pk_mul_f32 v[100:101], v[100:101], v[106:107]
	s_nop 0
	v_cvt_pk_bf16_f32 v99, v100, v101
	s_nop 0
	global_store_dwordx2 v[114:115], v[98:99], off offset:1056
	s_nop 0
	v_or_b32_e32 v98, 32, v0
	s_nop 0
	v_mad_i64_i32 v[98:99], s[0:1], v98, s35, v[126:127]
	s_nop 0
	v_lshl_add_u64 v[98:99], v[98:99], 0, v[128:129]
	s_nop 0
	global_load_dwordx2 v[100:101], v[98:99], off offset:1024
	v_rcp_f32_e32 v95, v95
	s_nop 0
	s_nop 0
	s_waitcnt vmcnt(0)
	s_nop 0
	v_lshlrev_b32_e32 v102, 16, v100
	v_rcp_f32_e32 v94, v94
	s_nop 0
	v_and_b32_e32 v103, 0xffff0000, v100
	v_pk_mul_f32 v[90:91], v[90:91], v[94:95]
	v_lshlrev_b32_e32 v100, 16, v101
	v_pk_mul_f32 v[90:91], v[90:91], v[102:103]
	v_and_b32_e32 v101, 0xffff0000, v101
	v_cvt_pk_bf16_f32 v90, v90, v91
	v_mul_f32_e32 v91, 0xbfb8aa3b, v96
	v_exp_f32_e32 v94, v91
	v_mul_f32_e32 v91, 0xbfb8aa3b, v97
	v_exp_f32_e32 v95, v91
	s_nop 0
	v_pk_add_f32 v[94:95], v[94:95], 1.0 op_sel_hi:[1,0]
	s_nop 0
	v_rcp_f32_e32 v95, v95
	s_nop 0
	v_rcp_f32_e32 v94, v94
	s_nop 0
	v_pk_mul_f32 v[92:93], v[92:93], v[94:95]
	s_nop 0
	v_pk_mul_f32 v[92:93], v[92:93], v[100:101]
	s_nop 0
	v_cvt_pk_bf16_f32 v91, v92, v93
	s_nop 0
	global_store_dwordx2 v[98:99], v[90:91], off offset:1024
	s_nop 0
	global_load_dwordx2 v[90:91], v[98:99], off offset:1056
	v_rcp_f32_e32 v87, v87
	s_nop 0
	s_nop 0
	s_waitcnt vmcnt(0)
	s_nop 0
	v_lshlrev_b32_e32 v92, 16, v90
	v_rcp_f32_e32 v86, v86
	s_nop 0
	v_and_b32_e32 v93, 0xffff0000, v90
	v_pk_mul_f32 v[82:83], v[82:83], v[86:87]
	v_lshlrev_b32_e32 v90, 16, v91
	v_pk_mul_f32 v[82:83], v[82:83], v[92:93]
	v_and_b32_e32 v91, 0xffff0000, v91
	v_cvt_pk_bf16_f32 v82, v82, v83
	v_mul_f32_e32 v83, 0xbfb8aa3b, v88
	v_exp_f32_e32 v86, v83
	v_mul_f32_e32 v83, 0xbfb8aa3b, v89
	v_exp_f32_e32 v87, v83
	s_nop 0
	v_pk_add_f32 v[86:87], v[86:87], 1.0 op_sel_hi:[1,0]
	s_nop 0
	v_rcp_f32_e32 v87, v87
	s_nop 0
	v_rcp_f32_e32 v86, v86
	s_nop 0
	v_pk_mul_f32 v[84:85], v[84:85], v[86:87]
	s_nop 0
	v_pk_mul_f32 v[84:85], v[84:85], v[90:91]
	s_nop 0
	v_cvt_pk_bf16_f32 v83, v84, v85
	s_nop 0
	global_store_dwordx2 v[98:99], v[82:83], off offset:1056
	s_nop 0
	v_or_b32_e32 v82, 48, v0
	s_nop 0
	v_mad_i64_i32 v[82:83], s[0:1], v82, s35, v[126:127]
	s_nop 0
	v_lshl_add_u64 v[82:83], v[82:83], 0, v[128:129]
	s_nop 0
	global_load_dwordx2 v[84:85], v[82:83], off offset:1024
	v_rcp_f32_e32 v79, v79
	s_nop 0
	s_nop 0
	s_waitcnt vmcnt(0)
	s_nop 0
	v_lshlrev_b32_e32 v86, 16, v84
	v_rcp_f32_e32 v78, v78
	s_nop 0
	v_and_b32_e32 v87, 0xffff0000, v84
	v_pk_mul_f32 v[74:75], v[74:75], v[78:79]
	v_lshlrev_b32_e32 v84, 16, v85
	v_pk_mul_f32 v[74:75], v[74:75], v[86:87]
	v_and_b32_e32 v85, 0xffff0000, v85
	v_cvt_pk_bf16_f32 v74, v74, v75
	v_mul_f32_e32 v75, 0xbfb8aa3b, v80
	v_exp_f32_e32 v78, v75
	v_mul_f32_e32 v75, 0xbfb8aa3b, v81
	v_exp_f32_e32 v79, v75
	s_nop 0
	v_pk_add_f32 v[78:79], v[78:79], 1.0 op_sel_hi:[1,0]
	s_nop 0
	v_rcp_f32_e32 v79, v79
	s_nop 0
	v_rcp_f32_e32 v78, v78
	s_nop 0
	v_pk_mul_f32 v[76:77], v[76:77], v[78:79]
	s_nop 0
	v_pk_mul_f32 v[76:77], v[76:77], v[84:85]
	s_nop 0
	v_cvt_pk_bf16_f32 v75, v76, v77
	s_nop 0
	global_store_dwordx2 v[82:83], v[74:75], off offset:1024
	s_nop 0
	global_load_dwordx2 v[74:75], v[82:83], off offset:1056
	v_rcp_f32_e32 v71, v71
	s_nop 0
	s_nop 0
	s_waitcnt vmcnt(0)
	s_nop 0
	v_lshlrev_b32_e32 v76, 16, v74
	v_rcp_f32_e32 v70, v70
	s_nop 0
	v_and_b32_e32 v77, 0xffff0000, v74
	v_pk_mul_f32 v[66:67], v[66:67], v[70:71]
	v_lshlrev_b32_e32 v74, 16, v75
	v_pk_mul_f32 v[66:67], v[66:67], v[76:77]
	v_and_b32_e32 v75, 0xffff0000, v75
	v_cvt_pk_bf16_f32 v66, v66, v67
	v_mul_f32_e32 v67, 0xbfb8aa3b, v72
	v_exp_f32_e32 v70, v67
	v_mul_f32_e32 v67, 0xbfb8aa3b, v73
	v_exp_f32_e32 v71, v67
	s_nop 0
	v_pk_add_f32 v[70:71], v[70:71], 1.0 op_sel_hi:[1,0]
	s_nop 0
	v_rcp_f32_e32 v71, v71
	s_nop 0
	v_rcp_f32_e32 v70, v70
	s_nop 0
	v_pk_mul_f32 v[68:69], v[68:69], v[70:71]
	s_nop 0
	v_pk_mul_f32 v[68:69], v[68:69], v[74:75]
	s_nop 0
	v_cvt_pk_bf16_f32 v67, v68, v69
	s_nop 0
	global_store_dwordx2 v[82:83], v[66:67], off offset:1056
	s_nop 0
	v_or_b32_e32 v66, 64, v0
	s_nop 0
	v_mad_i64_i32 v[66:67], s[0:1], v66, s35, v[126:127]
	s_nop 0
	v_lshl_add_u64 v[66:67], v[66:67], 0, v[128:129]
	s_nop 0
	global_load_dwordx2 v[68:69], v[66:67], off offset:1024
	v_rcp_f32_e32 v63, v63
	s_nop 0
	s_nop 0
	s_waitcnt vmcnt(0)
; DI unsigned pack2(float a, float b) { f2_t v = {a, b}; return __builtin_bit_cast(unsigned, __builtin_convertvector(v, bf2_t)); }
; DI float sigmoidf_(float x) { return 1.f / (1.f + __expf(-x)); }
; template <int EPI>
; DI void gemm_tile(const GemmArgs& ga, const EpiArgs& ea, int m0, int n0, char* lds) {
;     ...
;   } else if constexpr (EPI == EPI_GLU) {
;     const int blk = (n0 + wn * 64) >> 6;
; #pragma unroll
;     for (int mt = 0; mt < 8; ++mt) {
;       const int row = m0 + wm * 128 + mt * 16 + c16;
; #pragma unroll
;       for (int nt = 0; nt < 2; ++nt) {
;         const int j0 = blk * 32 + nt * 16 + quad * 4;
;         uint2* q = (uint2*)(p.proj + (size_t)row * PW + C_AG + j0);
;         const uint2 gv = *q;
;         const float g0 = __uint_as_float(gv.x << 16), g1 = __uint_as_float(gv.x & 0xffff0000u);
;         const float g2 = __uint_as_float(gv.y << 16), g3 = __uint_as_float(gv.y & 0xffff0000u);
;         uint2 o;
;         o.x = pack2(acc[mt][nt][0] * sigmoidf_(acc[mt][nt + 2][0]) * g0, acc[mt][nt][1] * sigmoidf_(acc[mt][nt + 2][1]) * g1);
;         o.y = pack2(acc[mt][nt][2] * sigmoidf_(acc[mt][nt + 2][2]) * g2, acc[mt][nt][3] * sigmoidf_(acc[mt][nt + 2][3]) * g3);
;         *q = o;
;       }
;     }
	s_nop 0
	v_lshlrev_b32_e32 v70, 16, v68
	v_rcp_f32_e32 v62, v62
	s_nop 0
	v_and_b32_e32 v71, 0xffff0000, v68
	v_pk_mul_f32 v[58:59], v[58:59], v[62:63]
	v_lshlrev_b32_e32 v68, 16, v69
	v_pk_mul_f32 v[58:59], v[58:59], v[70:71]
	v_and_b32_e32 v69, 0xffff0000, v69
	v_cvt_pk_bf16_f32 v58, v58, v59
	v_mul_f32_e32 v59, 0xbfb8aa3b, v64
	v_exp_f32_e32 v62, v59
	v_mul_f32_e32 v59, 0xbfb8aa3b, v65
	v_exp_f32_e32 v63, v59
	s_nop 0
	v_pk_add_f32 v[62:63], v[62:63], 1.0 op_sel_hi:[1,0]
	s_nop 0
	v_rcp_f32_e32 v63, v63
	s_nop 0
	v_rcp_f32_e32 v62, v62
	s_nop 0
	v_pk_mul_f32 v[60:61], v[60:61], v[62:63]
	s_nop 0
	v_pk_mul_f32 v[60:61], v[60:61], v[68:69]
	s_nop 0
	v_cvt_pk_bf16_f32 v59, v60, v61
	s_nop 0
	global_store_dwordx2 v[66:67], v[58:59], off offset:1024
	s_nop 0
	global_load_dwordx2 v[58:59], v[66:67], off offset:1056
	v_rcp_f32_e32 v55, v55
	s_nop 0
	s_nop 0
	s_waitcnt vmcnt(0)
	s_nop 0
	v_lshlrev_b32_e32 v60, 16, v58
	v_rcp_f32_e32 v54, v54
	s_nop 0
	v_and_b32_e32 v61, 0xffff0000, v58
	v_pk_mul_f32 v[50:51], v[50:51], v[54:55]
	v_lshlrev_b32_e32 v58, 16, v59
	v_pk_mul_f32 v[50:51], v[50:51], v[60:61]
	v_and_b32_e32 v59, 0xffff0000, v59
	v_cvt_pk_bf16_f32 v50, v50, v51
	v_mul_f32_e32 v51, 0xbfb8aa3b, v56
	v_exp_f32_e32 v54, v51
	v_mul_f32_e32 v51, 0xbfb8aa3b, v57
	v_exp_f32_e32 v55, v51
	s_nop 0
	v_pk_add_f32 v[54:55], v[54:55], 1.0 op_sel_hi:[1,0]
	s_nop 0
	v_rcp_f32_e32 v55, v55
	s_nop 0
	v_rcp_f32_e32 v54, v54
	s_nop 0
	v_pk_mul_f32 v[52:53], v[52:53], v[54:55]
	s_nop 0
	v_pk_mul_f32 v[52:53], v[52:53], v[58:59]
	s_nop 0
	v_cvt_pk_bf16_f32 v51, v52, v53
	s_nop 0
	global_store_dwordx2 v[66:67], v[50:51], off offset:1056
	s_nop 0
	v_or_b32_e32 v50, 0x50, v0
	s_nop 0
	v_mad_i64_i32 v[50:51], s[0:1], v50, s35, v[126:127]
	s_nop 0
	v_lshl_add_u64 v[50:51], v[50:51], 0, v[128:129]
	s_nop 0
	global_load_dwordx2 v[52:53], v[50:51], off offset:1024
	v_rcp_f32_e32 v47, v47
	s_nop 0
	s_nop 0
	s_waitcnt vmcnt(0)
	s_nop 0
	v_lshlrev_b32_e32 v54, 16, v52
	v_rcp_f32_e32 v46, v46
	s_nop 0
	v_and_b32_e32 v55, 0xffff0000, v52
	v_pk_mul_f32 v[42:43], v[42:43], v[46:47]
	v_lshlrev_b32_e32 v52, 16, v53
	v_pk_mul_f32 v[42:43], v[42:43], v[54:55]
	v_and_b32_e32 v53, 0xffff0000, v53
	v_cvt_pk_bf16_f32 v42, v42, v43
	v_mul_f32_e32 v43, 0xbfb8aa3b, v48
	v_exp_f32_e32 v46, v43
	v_mul_f32_e32 v43, 0xbfb8aa3b, v49
	v_exp_f32_e32 v47, v43
	s_nop 0
	v_pk_add_f32 v[46:47], v[46:47], 1.0 op_sel_hi:[1,0]
	s_nop 0
	v_rcp_f32_e32 v47, v47
	s_nop 0
	v_rcp_f32_e32 v46, v46
	s_nop 0
	v_pk_mul_f32 v[44:45], v[44:45], v[46:47]
	s_nop 0
	v_pk_mul_f32 v[44:45], v[44:45], v[52:53]
	s_nop 0
	v_cvt_pk_bf16_f32 v43, v44, v45
	s_nop 0
	global_store_dwordx2 v[50:51], v[42:43], off offset:1024
	s_nop 0
	global_load_dwordx2 v[42:43], v[50:51], off offset:1056
	v_rcp_f32_e32 v39, v39
	s_nop 0
	s_nop 0
	s_waitcnt vmcnt(0)
	s_nop 0
	v_lshlrev_b32_e32 v44, 16, v42
	v_rcp_f32_e32 v38, v38
	s_nop 0
	v_and_b32_e32 v45, 0xffff0000, v42
	v_pk_mul_f32 v[34:35], v[34:35], v[38:39]
	v_lshlrev_b32_e32 v42, 16, v43
	v_pk_mul_f32 v[34:35], v[34:35], v[44:45]
	v_and_b32_e32 v43, 0xffff0000, v43
	v_cvt_pk_bf16_f32 v34, v34, v35
	v_mul_f32_e32 v35, 0xbfb8aa3b, v40
	v_exp_f32_e32 v38, v35
	v_mul_f32_e32 v35, 0xbfb8aa3b, v41
	v_exp_f32_e32 v39, v35
	s_nop 0
	v_pk_add_f32 v[38:39], v[38:39], 1.0 op_sel_hi:[1,0]
	s_nop 0
	v_rcp_f32_e32 v39, v39
	s_nop 0
	v_rcp_f32_e32 v38, v38
	s_nop 0
	v_pk_mul_f32 v[36:37], v[36:37], v[38:39]
	s_nop 0
	v_pk_mul_f32 v[36:37], v[36:37], v[42:43]
	s_nop 0
	v_cvt_pk_bf16_f32 v35, v36, v37
	s_nop 0
	global_store_dwordx2 v[50:51], v[34:35], off offset:1056
	s_nop 0
	v_or_b32_e32 v34, 0x60, v0
	s_nop 0
	v_mad_i64_i32 v[34:35], s[0:1], v34, s35, v[126:127]
	s_nop 0
	v_lshl_add_u64 v[34:35], v[34:35], 0, v[128:129]
	s_nop 0
	global_load_dwordx2 v[36:37], v[34:35], off offset:1024
	v_rcp_f32_e32 v31, v31
	s_nop 0
	s_nop 0
	v_or_b32_e32 v0, 0x70, v0
	v_rcp_f32_e32 v30, v30
	s_nop 0
	v_pk_mul_f32 v[26:27], v[26:27], v[30:31]
	s_waitcnt vmcnt(0)
; DI unsigned pack2(float a, float b) { f2_t v = {a, b}; return __builtin_bit_cast(unsigned, __builtin_convertvector(v, bf2_t)); }
; DI float sigmoidf_(float x) { return 1.f / (1.f + __expf(-x)); }
; template <int EPI>
; DI void gemm_tile(const GemmArgs& ga, const EpiArgs& ea, int m0, int n0, char* lds) {
;     ...
;   } else if constexpr (EPI == EPI_GLU) {
;     const int blk = (n0 + wn * 64) >> 6;
; #pragma unroll
;     for (int mt = 0; mt < 8; ++mt) {
;       const int row = m0 + wm * 128 + mt * 16 + c16;
; #pragma unroll
;       for (int nt = 0; nt < 2; ++nt) {
;         const int j0 = blk * 32 + nt * 16 + quad * 4;
;         uint2* q = (uint2*)(p.proj + (size_t)row * PW + C_AG + j0);
;         const uint2 gv = *q;
;         const float g0 = __uint_as_float(gv.x << 16), g1 = __uint_as_float(gv.x & 0xffff0000u);
;         const float g2 = __uint_as_float(gv.y << 16), g3 = __uint_as_float(gv.y & 0xffff0000u);
;         uint2 o;
;         o.x = pack2(acc[mt][nt][0] * sigmoidf_(acc[mt][nt + 2][0]) * g0, acc[mt][nt][1] * sigmoidf_(acc[mt][nt + 2][1]) * g1);
;         o.y = pack2(acc[mt][nt][2] * sigmoidf_(acc[mt][nt + 2][2]) * g2, acc[mt][nt][3] * sigmoidf_(acc[mt][nt + 2][3]) * g3);
;         *q = o;
;       }
;     }
	v_lshlrev_b32_e32 v38, 16, v36
	v_and_b32_e32 v39, 0xffff0000, v36
	v_pk_mul_f32 v[26:27], v[26:27], v[38:39]
	v_lshlrev_b32_e32 v36, 16, v37
	v_cvt_pk_bf16_f32 v26, v26, v27
	v_mul_f32_e32 v27, 0xbfb8aa3b, v32
	v_exp_f32_e32 v30, v27
	v_mul_f32_e32 v27, 0xbfb8aa3b, v33
	v_exp_f32_e32 v31, v27
	v_and_b32_e32 v37, 0xffff0000, v37
	v_pk_add_f32 v[30:31], v[30:31], 1.0 op_sel_hi:[1,0]
	s_nop 0
	v_rcp_f32_e32 v31, v31
	s_nop 0
	v_rcp_f32_e32 v30, v30
	s_nop 0
	v_pk_mul_f32 v[28:29], v[28:29], v[30:31]
	s_nop 0
	v_pk_mul_f32 v[28:29], v[28:29], v[36:37]
	s_nop 0
	v_cvt_pk_bf16_f32 v27, v28, v29
	s_nop 0
	global_store_dwordx2 v[34:35], v[26:27], off offset:1024
	s_nop 0
	global_load_dwordx2 v[26:27], v[34:35], off offset:1056
	v_rcp_f32_e32 v23, v23
	s_nop 0
	s_nop 0
	s_waitcnt vmcnt(0)
	s_nop 0
	v_lshlrev_b32_e32 v28, 16, v26
	v_rcp_f32_e32 v22, v22
	s_nop 0
	v_and_b32_e32 v29, 0xffff0000, v26
	v_pk_mul_f32 v[18:19], v[18:19], v[22:23]
	v_lshlrev_b32_e32 v26, 16, v27
	v_pk_mul_f32 v[18:19], v[18:19], v[28:29]
	v_and_b32_e32 v27, 0xffff0000, v27
	v_cvt_pk_bf16_f32 v18, v18, v19
	v_mul_f32_e32 v19, 0xbfb8aa3b, v24
	v_exp_f32_e32 v22, v19
	v_mul_f32_e32 v19, 0xbfb8aa3b, v25
	v_exp_f32_e32 v23, v19
	s_nop 0
	v_pk_add_f32 v[22:23], v[22:23], 1.0 op_sel_hi:[1,0]
	s_nop 0
	v_rcp_f32_e32 v23, v23
	s_nop 0
	v_rcp_f32_e32 v22, v22
	s_nop 0
	v_pk_mul_f32 v[20:21], v[20:21], v[22:23]
	s_nop 0
	v_pk_mul_f32 v[20:21], v[20:21], v[26:27]
	s_nop 0
	v_cvt_pk_bf16_f32 v19, v20, v21
	global_store_dwordx2 v[34:35], v[18:19], off offset:1056
	v_mad_i64_i32 v[18:19], s[0:1], v0, s35, v[126:127]
	v_lshl_add_u64 v[18:19], v[18:19], 0, v[128:129]
	global_load_dwordx2 v[20:21], v[18:19], off offset:1024
	v_mul_f32_e32 v0, 0xbfb8aa3b, v14
	v_exp_f32_e32 v14, v0
	v_mul_f32_e32 v0, 0xbfb8aa3b, v15
	v_exp_f32_e32 v15, v0
	s_waitcnt vmcnt(0)
	v_lshlrev_b32_e32 v22, 16, v20
	v_pk_add_f32 v[14:15], v[14:15], 1.0 op_sel_hi:[1,0]
	v_and_b32_e32 v23, 0xffff0000, v20
	s_nop 0
	v_lshlrev_b32_e32 v20, 16, v21
	s_nop 0
	v_and_b32_e32 v21, 0xffff0000, v21
	v_rcp_f32_e32 v15, v15
	s_nop 0
	v_rcp_f32_e32 v14, v14
	s_nop 0
	v_mul_f32_e32 v0, 0xbfb8aa3b, v16
	v_pk_mul_f32 v[10:11], v[10:11], v[14:15]
	v_exp_f32_e32 v14, v0
	v_mul_f32_e32 v0, 0xbfb8aa3b, v17
	v_exp_f32_e32 v15, v0
	v_pk_mul_f32 v[10:11], v[10:11], v[22:23]
	v_pk_add_f32 v[14:15], v[14:15], 1.0 op_sel_hi:[1,0]
	s_nop 0
	s_nop 0
	v_cvt_pk_bf16_f32 v10, v10, v11
	v_rcp_f32_e32 v15, v15
	s_nop 0
	v_rcp_f32_e32 v14, v14
	s_nop 0
	v_pk_mul_f32 v[12:13], v[12:13], v[14:15]
	v_mul_f32_e32 v0, 0xbfb8aa3b, v6
	v_pk_mul_f32 v[12:13], v[12:13], v[20:21]
	v_exp_f32_e32 v6, v0
	v_cvt_pk_bf16_f32 v11, v12, v13
	global_store_dwordx2 v[18:19], v[10:11], off offset:1024
	global_load_dwordx2 v[10:11], v[18:19], off offset:1056
	v_mul_f32_e32 v0, 0xbfb8aa3b, v7
	v_exp_f32_e32 v7, v0
	s_waitcnt vmcnt(0)
	v_lshlrev_b32_e32 v12, 16, v10
	v_pk_add_f32 v[6:7], v[6:7], 1.0 op_sel_hi:[1,0]
	v_and_b32_e32 v13, 0xffff0000, v10
	s_nop 0
	v_lshlrev_b32_e32 v10, 16, v11
	s_nop 0
	v_and_b32_e32 v11, 0xffff0000, v11
	v_rcp_f32_e32 v7, v7
	s_nop 0
	v_rcp_f32_e32 v6, v6
	s_nop 0
	v_mul_f32_e32 v0, 0xbfb8aa3b, v8
	v_pk_mul_f32 v[2:3], v[2:3], v[6:7]
	v_exp_f32_e32 v6, v0
	v_mul_f32_e32 v0, 0xbfb8aa3b, v9
	v_exp_f32_e32 v7, v0
	v_pk_mul_f32 v[2:3], v[2:3], v[12:13]
	v_pk_add_f32 v[6:7], v[6:7], 1.0 op_sel_hi:[1,0]
	s_nop 0
	s_nop 0
	v_cvt_pk_bf16_f32 v2, v2, v3
	v_rcp_f32_e32 v7, v7
	s_nop 0
	s_nop 0
	s_mov_b64 s[0:1], 0
	v_rcp_f32_e32 v6, v6
	s_nop 0
	v_pk_mul_f32 v[4:5], v[4:5], v[6:7]
	s_nop 0
	v_pk_mul_f32 v[4:5], v[4:5], v[10:11]
	s_nop 0
	v_cvt_pk_bf16_f32 v3, v4, v5
	global_store_dwordx2 v[18:19], v[2:3], off offset:1056
	s_branch .LBB0_1427
